# speedup vs baseline: 1.0057x; 1.0057x over previous
.LBB0_91:
	v_mul_lo_u32 v64, v71, s82
	v_lshlrev_b32_e32 v66, 4, v68
	v_add_u32_e32 v64, 0x20000, v64
	v_and_b32_e32 v66, 0x70, v66
	v_mul_u32_u24_e32 v67, 0x90, v69
	v_bfe_u32 v65, v68, 3, 3
	v_add3_u32 v67, v64, v67, v72
	v_or_b32_e32 v64, v64, v66
	v_or3_b32 v68, v70, s64, v65
	v_mad_u32_u24 v69, v65, s83, v64
	s_waitcnt vmcnt(14)
	v_pk_mul_f32 v[62:63], v[172:173], v[62:63] op_sel_hi:[0,1]
	v_pk_mul_f32 v[60:61], v[172:173], v[60:61] op_sel_hi:[0,1]
	v_pk_mul_f32 v[64:65], v[172:173], v[58:59] op_sel_hi:[0,1]
	v_pk_mul_f32 v[58:59], v[172:173], v[56:57] op_sel_hi:[0,1]
	v_cvt_pk_bf16_f32 v56, v60, v61
	v_cvt_pk_bf16_f32 v57, v62, v63
	v_cvt_pk_bf16_f32 v58, v58, v59
	v_cvt_pk_bf16_f32 v59, v64, v65
	ds_write_b128 v67, v[56:59]
	v_pk_mul_f32 v[56:57], v[172:173], v[50:51] op_sel_hi:[0,1]
	v_pk_mul_f32 v[50:51], v[172:173], v[48:49] op_sel_hi:[0,1]
	v_pk_mul_f32 v[54:55], v[172:173], v[54:55] op_sel_hi:[0,1]
	v_pk_mul_f32 v[52:53], v[172:173], v[52:53] op_sel_hi:[0,1]
	v_cvt_pk_bf16_f32 v48, v52, v53
	v_cvt_pk_bf16_f32 v49, v54, v55
	v_cvt_pk_bf16_f32 v50, v50, v51
	v_cvt_pk_bf16_f32 v51, v56, v57
	ds_write_b128 v67, v[48:51] offset:64
	ds_read_b128 v[48:51], v69
	s_lshl_b32 s62, s89, 9
	v_or3_b32 v52, v73, s62, v66
	v_lshl_add_u32 v56, v68, 12, v52
	v_add_u32_e32 v57, 0x80000, v56
	ds_read_b128 v[52:55], v69 offset:1152
	s_waitcnt lgkmcnt(0)
	global_store_dwordx4 v57, v[48:51], s[6:7]
	v_pk_mul_f32 v[46:47], v[170:171], v[46:47] op_sel_hi:[0,1]
	v_pk_mul_f32 v[44:45], v[170:171], v[44:45] op_sel_hi:[0,1]
	v_pk_mul_f32 v[48:49], v[170:171], v[42:43] op_sel_hi:[0,1]
	v_pk_mul_f32 v[42:43], v[170:171], v[40:41] op_sel_hi:[0,1]
	v_cvt_pk_bf16_f32 v40, v44, v45
	v_cvt_pk_bf16_f32 v41, v46, v47
	v_cvt_pk_bf16_f32 v42, v42, v43
	v_cvt_pk_bf16_f32 v43, v48, v49
	ds_write_b128 v67, v[40:43]
	v_pk_mul_f32 v[40:41], v[170:171], v[34:35] op_sel_hi:[0,1]
	v_pk_mul_f32 v[34:35], v[170:171], v[32:33] op_sel_hi:[0,1]
	v_pk_mul_f32 v[38:39], v[170:171], v[38:39] op_sel_hi:[0,1]
	v_pk_mul_f32 v[36:37], v[170:171], v[36:37] op_sel_hi:[0,1]
	v_cvt_pk_bf16_f32 v32, v36, v37
	v_cvt_pk_bf16_f32 v33, v38, v39
	v_cvt_pk_bf16_f32 v34, v34, v35
	v_cvt_pk_bf16_f32 v35, v40, v41
	ds_write_b128 v67, v[32:35] offset:64
	ds_read_b128 v[32:35], v69
	v_add_u32_e32 v36, 0x88000, v56
	v_add_u32_e32 v40, 0x90000, v56
	global_store_dwordx4 v36, v[52:55], s[6:7]
	ds_read_b128 v[36:39], v69 offset:1152
	s_waitcnt lgkmcnt(1)
	global_store_dwordx4 v40, v[32:35], s[6:7]
	v_pk_mul_f32 v[30:31], v[168:169], v[30:31] op_sel_hi:[0,1]
	v_pk_mul_f32 v[28:29], v[168:169], v[28:29] op_sel_hi:[0,1]
	v_pk_mul_f32 v[32:33], v[168:169], v[26:27] op_sel_hi:[0,1]
	v_pk_mul_f32 v[26:27], v[168:169], v[24:25] op_sel_hi:[0,1]
	v_cvt_pk_bf16_f32 v24, v28, v29
	v_cvt_pk_bf16_f32 v25, v30, v31
	v_cvt_pk_bf16_f32 v26, v26, v27
	v_cvt_pk_bf16_f32 v27, v32, v33
	ds_write_b128 v67, v[24:27]
	v_pk_mul_f32 v[24:25], v[168:169], v[18:19] op_sel_hi:[0,1]
	v_pk_mul_f32 v[18:19], v[168:169], v[16:17] op_sel_hi:[0,1]
	v_pk_mul_f32 v[22:23], v[168:169], v[22:23] op_sel_hi:[0,1]
	v_pk_mul_f32 v[20:21], v[168:169], v[20:21] op_sel_hi:[0,1]
	v_cvt_pk_bf16_f32 v16, v20, v21
	v_cvt_pk_bf16_f32 v17, v22, v23
	v_cvt_pk_bf16_f32 v18, v18, v19
	v_cvt_pk_bf16_f32 v19, v24, v25
	ds_write_b128 v67, v[16:19] offset:64
	ds_read_b128 v[16:19], v69
	v_add_u32_e32 v20, 0x98000, v56
	v_add_u32_e32 v24, 0xa0000, v56
	s_waitcnt lgkmcnt(3)
	global_store_dwordx4 v20, v[36:39], s[6:7]
	ds_read_b128 v[20:23], v69 offset:1152
	s_waitcnt lgkmcnt(1)
	global_store_dwordx4 v24, v[16:19], s[6:7]
	v_pk_mul_f32 v[14:15], v[166:167], v[14:15] op_sel_hi:[0,1]
	v_pk_mul_f32 v[12:13], v[166:167], v[12:13] op_sel_hi:[0,1]
	v_pk_mul_f32 v[16:17], v[166:167], v[10:11] op_sel_hi:[0,1]
	v_pk_mul_f32 v[10:11], v[166:167], v[8:9] op_sel_hi:[0,1]
	v_cvt_pk_bf16_f32 v8, v12, v13
	v_cvt_pk_bf16_f32 v9, v14, v15
	v_cvt_pk_bf16_f32 v10, v10, v11
	v_cvt_pk_bf16_f32 v11, v16, v17
	ds_write_b128 v67, v[8:11]
	v_pk_mul_f32 v[8:9], v[166:167], v[2:3] op_sel_hi:[0,1]
	v_pk_mul_f32 v[2:3], v[166:167], v[0:1] op_sel_hi:[0,1]
	v_pk_mul_f32 v[6:7], v[166:167], v[6:7] op_sel_hi:[0,1]
	v_pk_mul_f32 v[4:5], v[166:167], v[4:5] op_sel_hi:[0,1]
	v_cvt_pk_bf16_f32 v0, v4, v5
	v_cvt_pk_bf16_f32 v1, v6, v7
	v_cvt_pk_bf16_f32 v2, v2, v3
	v_cvt_pk_bf16_f32 v3, v8, v9
	ds_write_b128 v67, v[0:3] offset:64
	ds_read_b128 v[0:3], v69
	ds_read_b128 v[64:67], v69 offset:1152
	v_add_u32_e32 v4, 0xa8000, v56
	s_waitcnt lgkmcnt(4)
	global_store_dwordx4 v4, v[20:23], s[6:7]
	v_add_u32_e32 v4, 0xb0000, v56
	v_add_u32_e32 v74, 0xb8000, v56
	s_waitcnt lgkmcnt(1)
	global_store_dwordx4 v4, v[0:3], s[6:7]

.LBB0_125:
	v_mbcnt_lo_u32_b32 v68, -1, 0
	v_mbcnt_hi_u32_b32 v68, -1, v68
	s_mov_b64 s[72:73], -1
	v_add_u32_e32 v64, s76, v68
	v_bfe_u32 v65, v64, 8, 1
	v_ashrrev_i32_e32 v71, 6, v64
	v_bfe_u32 v64, v68, 4, 2
	v_and_b32_e32 v73, 3, v71
	v_and_b32_e32 v69, 15, v68
	s_cmp_gt_i32 s74, 1
	v_lshlrev_b32_e32 v70, 6, v65
	v_lshlrev_b32_e32 v72, 4, v64
	s_cbranch_scc0 .LBB0_127
	v_lshlrev_b32_e32 v64, 6, v73
	v_or3_b32 v65, v70, s64, v69
	v_or3_b32 v64, v64, v72, s62
	v_lshl_add_u32 v80, v65, 12, v64
	s_waitcnt vmcnt(14)
	v_mul_f32_e32 v64, v172, v172
	v_pk_mul_f32 v[74:75], v[64:65], v[60:61] op_sel_hi:[0,1]
	v_pk_mul_f32 v[66:67], v[64:65], v[62:63] op_sel_hi:[0,1]
	v_pk_mul_f32 v[76:77], v[64:65], v[54:55] op_sel_hi:[0,1]
	v_pk_mul_f32 v[78:79], v[64:65], v[52:53] op_sel_hi:[0,1]
	v_mul_f32_e32 v64, v56, v74
	v_mul_f32_e32 v65, v57, v75
	v_cvt_pk_bf16_f32 v64, v64, v65
	v_mul_f32_e32 v65, v58, v66
	v_mul_f32_e32 v66, v59, v67
	v_cvt_pk_bf16_f32 v65, v65, v66
	v_mul_f32_e32 v66, v48, v78
	v_mul_f32_e32 v67, v49, v79
	v_add_u32_e32 v81, 0x80000, v80
	v_cvt_pk_bf16_f32 v66, v66, v67
	v_mul_f32_e32 v67, v50, v76
	v_mul_f32_e32 v74, v51, v77
	v_cvt_pk_bf16_f32 v67, v67, v74
	global_store_dwordx4 v81, v[64:67], s[6:7]
	v_add_u32_e32 v81, 0x90000, v80
	s_mov_b64 s[72:73], 0
	v_mul_f32_e32 v64, v170, v170
	v_pk_mul_f32 v[74:75], v[64:65], v[44:45] op_sel_hi:[0,1]
	v_pk_mul_f32 v[66:67], v[64:65], v[46:47] op_sel_hi:[0,1]
	v_pk_mul_f32 v[76:77], v[64:65], v[38:39] op_sel_hi:[0,1]
	v_pk_mul_f32 v[78:79], v[64:65], v[36:37] op_sel_hi:[0,1]
	v_mul_f32_e32 v64, v40, v74
	v_mul_f32_e32 v65, v41, v75
	v_cvt_pk_bf16_f32 v64, v64, v65
	v_mul_f32_e32 v65, v42, v66
	v_mul_f32_e32 v66, v43, v67
	v_cvt_pk_bf16_f32 v65, v65, v66
	v_mul_f32_e32 v66, v32, v78
	v_mul_f32_e32 v67, v33, v79
	v_cvt_pk_bf16_f32 v66, v66, v67
	v_mul_f32_e32 v67, v34, v76
	v_mul_f32_e32 v74, v35, v77
	v_cvt_pk_bf16_f32 v67, v67, v74
	global_store_dwordx4 v81, v[64:67], s[6:7]
	v_add_u32_e32 v81, 0xa0000, v80
	s_nop 0
	v_mul_f32_e32 v64, v168, v168
	v_pk_mul_f32 v[74:75], v[64:65], v[28:29] op_sel_hi:[0,1]
	v_pk_mul_f32 v[66:67], v[64:65], v[30:31] op_sel_hi:[0,1]
	v_pk_mul_f32 v[76:77], v[64:65], v[22:23] op_sel_hi:[0,1]
	v_pk_mul_f32 v[78:79], v[64:65], v[20:21] op_sel_hi:[0,1]
	v_mul_f32_e32 v64, v24, v74
	v_mul_f32_e32 v65, v25, v75
	v_cvt_pk_bf16_f32 v64, v64, v65
	v_mul_f32_e32 v65, v26, v66
	v_mul_f32_e32 v66, v27, v67
	v_cvt_pk_bf16_f32 v65, v65, v66
	v_mul_f32_e32 v66, v16, v78
	v_mul_f32_e32 v67, v17, v79
	v_cvt_pk_bf16_f32 v66, v66, v67
	v_mul_f32_e32 v67, v18, v76
	v_mul_f32_e32 v74, v19, v77
	v_cvt_pk_bf16_f32 v67, v67, v74
	global_store_dwordx4 v81, v[64:67], s[6:7]
	v_add_u32_e32 v74, 0xb0000, v80
	s_nop 0
	v_mul_f32_e32 v64, v166, v166
	v_pk_mul_f32 v[76:77], v[64:65], v[12:13] op_sel_hi:[0,1]
	v_pk_mul_f32 v[66:67], v[64:65], v[14:15] op_sel_hi:[0,1]
	v_pk_mul_f32 v[78:79], v[64:65], v[6:7] op_sel_hi:[0,1]
	v_pk_mul_f32 v[80:81], v[64:65], v[4:5] op_sel_hi:[0,1]
	v_mul_f32_e32 v64, v8, v76
	v_mul_f32_e32 v65, v9, v77
	v_cvt_pk_bf16_f32 v64, v64, v65
	v_mul_f32_e32 v65, v10, v66
	v_mul_f32_e32 v66, v11, v67
	v_cvt_pk_bf16_f32 v65, v65, v66
	v_mul_f32_e32 v66, v0, v80
	v_mul_f32_e32 v67, v1, v81
	v_cvt_pk_bf16_f32 v66, v66, v67
	v_mul_f32_e32 v67, v2, v78
	v_mul_f32_e32 v75, v3, v79
	v_cvt_pk_bf16_f32 v67, v67, v75
.LBB0_127:
	s_andn2_b64 vcc, exec, s[72:73]
	s_cbranch_vccnz .LBB0_92
	s_cmp_lg_u32 s74, 0
	v_lshlrev_b32_e32 v73, 7, v73
	s_cbranch_scc0 .LBB0_133
	s_lshl_b32 s62, s89, 9
	v_or3_b32 v64, v70, v69, s64
	v_or3_b32 v65, v72, s62, v73
	v_lshl_add_u32 v78, v64, 12, v65
	s_waitcnt vmcnt(14)
	v_pk_mul_f32 v[66:67], v[172:173], v[62:63] op_sel_hi:[0,1]
	v_pk_mul_f32 v[64:65], v[172:173], v[60:61] op_sel_hi:[0,1]
	v_add_u32_e32 v79, 0x80000, v78
	v_pk_mul_f32 v[74:75], v[172:173], v[58:59] op_sel_hi:[0,1]
	v_pk_mul_f32 v[76:77], v[172:173], v[56:57] op_sel_hi:[0,1]
	v_cvt_pk_bf16_f32 v64, v64, v65
	v_cvt_pk_bf16_f32 v65, v66, v67
	v_cvt_pk_bf16_f32 v66, v76, v77
	v_cvt_pk_bf16_f32 v67, v74, v75
	global_store_dwordx4 v79, v[64:67], s[6:7]
	v_pk_mul_f32 v[74:75], v[172:173], v[50:51] op_sel_hi:[0,1]
	v_pk_mul_f32 v[76:77], v[172:173], v[48:49] op_sel_hi:[0,1]
	v_pk_mul_f32 v[66:67], v[172:173], v[54:55] op_sel_hi:[0,1]
	v_pk_mul_f32 v[64:65], v[172:173], v[52:53] op_sel_hi:[0,1]
	v_cvt_pk_bf16_f32 v64, v64, v65
	v_cvt_pk_bf16_f32 v65, v66, v67
	v_cvt_pk_bf16_f32 v66, v76, v77
	v_cvt_pk_bf16_f32 v67, v74, v75
	v_add_u32_e32 v74, 0x80040, v78
	global_store_dwordx4 v74, v[64:67], s[6:7]
	v_add_u32_e32 v79, 0x90000, v78
	v_pk_mul_f32 v[74:75], v[170:171], v[42:43] op_sel_hi:[0,1]
	v_pk_mul_f32 v[66:67], v[170:171], v[46:47] op_sel_hi:[0,1]
	v_pk_mul_f32 v[64:65], v[170:171], v[44:45] op_sel_hi:[0,1]
	v_pk_mul_f32 v[76:77], v[170:171], v[40:41] op_sel_hi:[0,1]
	v_cvt_pk_bf16_f32 v64, v64, v65
	v_cvt_pk_bf16_f32 v65, v66, v67
	v_cvt_pk_bf16_f32 v66, v76, v77
	v_cvt_pk_bf16_f32 v67, v74, v75
	global_store_dwordx4 v79, v[64:67], s[6:7]
	v_pk_mul_f32 v[74:75], v[170:171], v[34:35] op_sel_hi:[0,1]
	v_pk_mul_f32 v[76:77], v[170:171], v[32:33] op_sel_hi:[0,1]
	v_pk_mul_f32 v[66:67], v[170:171], v[38:39] op_sel_hi:[0,1]
	v_pk_mul_f32 v[64:65], v[170:171], v[36:37] op_sel_hi:[0,1]
	v_cvt_pk_bf16_f32 v64, v64, v65
	v_cvt_pk_bf16_f32 v65, v66, v67
	v_cvt_pk_bf16_f32 v66, v76, v77
	v_cvt_pk_bf16_f32 v67, v74, v75
	v_add_u32_e32 v74, 0x90040, v78
	global_store_dwordx4 v74, v[64:67], s[6:7]
	v_add_u32_e32 v79, 0xa0000, v78
	v_pk_mul_f32 v[74:75], v[168:169], v[26:27] op_sel_hi:[0,1]
	v_pk_mul_f32 v[66:67], v[168:169], v[30:31] op_sel_hi:[0,1]
	v_pk_mul_f32 v[64:65], v[168:169], v[28:29] op_sel_hi:[0,1]
	v_pk_mul_f32 v[76:77], v[168:169], v[24:25] op_sel_hi:[0,1]
	v_cvt_pk_bf16_f32 v64, v64, v65
	v_cvt_pk_bf16_f32 v65, v66, v67
	v_cvt_pk_bf16_f32 v66, v76, v77
	v_cvt_pk_bf16_f32 v67, v74, v75
	global_store_dwordx4 v79, v[64:67], s[6:7]
	v_pk_mul_f32 v[74:75], v[168:169], v[18:19] op_sel_hi:[0,1]
	v_pk_mul_f32 v[76:77], v[168:169], v[16:17] op_sel_hi:[0,1]
	v_pk_mul_f32 v[66:67], v[168:169], v[22:23] op_sel_hi:[0,1]
	v_pk_mul_f32 v[64:65], v[168:169], v[20:21] op_sel_hi:[0,1]
	v_cvt_pk_bf16_f32 v64, v64, v65
	v_cvt_pk_bf16_f32 v65, v66, v67
	v_cvt_pk_bf16_f32 v66, v76, v77
	v_cvt_pk_bf16_f32 v67, v74, v75
	v_add_u32_e32 v74, 0xa0040, v78
	global_store_dwordx4 v74, v[64:67], s[6:7]
	v_add_u32_e32 v79, 0xb0000, v78
	v_pk_mul_f32 v[74:75], v[166:167], v[10:11] op_sel_hi:[0,1]
	v_pk_mul_f32 v[66:67], v[166:167], v[14:15] op_sel_hi:[0,1]
	v_pk_mul_f32 v[64:65], v[166:167], v[12:13] op_sel_hi:[0,1]
	v_pk_mul_f32 v[76:77], v[166:167], v[8:9] op_sel_hi:[0,1]
	v_cvt_pk_bf16_f32 v64, v64, v65
	v_cvt_pk_bf16_f32 v65, v66, v67
	v_cvt_pk_bf16_f32 v66, v76, v77
	v_cvt_pk_bf16_f32 v67, v74, v75
	global_store_dwordx4 v79, v[64:67], s[6:7]
	v_pk_mul_f32 v[74:75], v[166:167], v[2:3] op_sel_hi:[0,1]
	v_pk_mul_f32 v[76:77], v[166:167], v[0:1] op_sel_hi:[0,1]
	v_pk_mul_f32 v[66:67], v[166:167], v[6:7] op_sel_hi:[0,1]
	v_pk_mul_f32 v[64:65], v[166:167], v[4:5] op_sel_hi:[0,1]
	v_cvt_pk_bf16_f32 v64, v64, v65
	v_cvt_pk_bf16_f32 v65, v66, v67
	v_cvt_pk_bf16_f32 v66, v76, v77
	v_cvt_pk_bf16_f32 v67, v74, v75
	v_add_u32_e32 v74, 0xb0040, v78
	s_cbranch_execnz .LBB0_92
	s_branch .LBB0_91

.LBB0_244:
	v_mbcnt_lo_u32_b32 v69, -1, 0
	v_mbcnt_hi_u32_b32 v69, -1, v69
	s_and_b64 vcc, exec, s[58:59]
	v_add_u32_e32 v64, s64, v69
	v_bfe_u32 v68, v64, 8, 1
	v_ashrrev_i32_e32 v73, 6, v64
	v_bfe_u32 v64, v69, 4, 2
	v_and_b32_e32 v71, 3, v73
	v_and_b32_e32 v70, 15, v69
	v_lshlrev_b32_e32 v72, 4, v64
	s_cbranch_vccz .LBB0_247
	s_lshl_b32 s57, s82, 14
	s_lshl_b32 s58, s80, 22
	s_add_i32 s57, s57, s58
	v_lshlrev_b32_e32 v64, 6, v70
	v_or3_b32 v64, s57, v64, v72
	v_lshl_add_u32 v64, v71, 20, v64
	v_lshl_or_b32 v164, v68, 12, v64
	s_waitcnt vmcnt(14)
	v_pk_mul_f32 v[64:65], v[172:173], v[58:59] op_sel_hi:[0,1]
	v_pk_mul_f32 v[66:67], v[172:173], v[56:57] op_sel_hi:[0,1]
	v_max_f32_e32 v66, 0, v66
	v_max_f32_e32 v64, 0, v64
	v_mul_f32_e32 v74, v66, v66
	v_max_f32_e32 v66, 0, v67
	v_mul_f32_e32 v76, v64, v64
	v_max_f32_e32 v64, 0, v65
	v_mul_f32_e32 v75, v66, v66
	v_mul_f32_e32 v77, v64, v64
	v_pk_mul_f32 v[64:65], v[172:173], v[62:63] op_sel_hi:[0,1]
	v_pk_mul_f32 v[66:67], v[172:173], v[60:61] op_sel_hi:[0,1]
	v_max_f32_e32 v66, 0, v66
	v_max_f32_e32 v64, 0, v64
	v_mul_f32_e32 v66, v66, v66
	v_max_f32_e32 v67, 0, v67
	v_mul_f32_e32 v78, v64, v64
	v_max_f32_e32 v64, 0, v65
	v_mul_f32_e32 v67, v67, v67
	v_mul_f32_e32 v65, v64, v64
	v_cvt_pk_bf16_f32 v64, v66, v67
	v_cvt_pk_bf16_f32 v66, v74, v75
	v_lshl_add_u64 v[74:75], s[0:1], 0, v[164:165]
	v_cvt_pk_bf16_f32 v67, v76, v77
	v_add_co_u32_e32 v76, vcc, s68, v74
	v_cvt_pk_bf16_f32 v65, v78, v65
	s_nop 1
	v_addc_co_u32_e32 v77, vcc, 0, v75, vcc
	global_store_dwordx4 v[76:77], v[64:67], off
	v_add_co_u32_e32 v74, vcc, s77, v74
	s_nop 0
	v_pk_mul_f32 v[64:65], v[172:173], v[50:51] op_sel_hi:[0,1]
	v_max_f32_e32 v64, 0, v64
	v_pk_mul_f32 v[66:67], v[172:173], v[48:49] op_sel_hi:[0,1]
	v_mul_f32_e32 v80, v64, v64
	v_max_f32_e32 v64, 0, v65
	v_max_f32_e32 v66, 0, v66
	v_mul_f32_e32 v81, v64, v64
	v_pk_mul_f32 v[64:65], v[172:173], v[54:55] op_sel_hi:[0,1]
	v_mul_f32_e32 v78, v66, v66
	v_max_f32_e32 v66, 0, v67
	v_max_f32_e32 v64, 0, v64
	v_mul_f32_e32 v79, v66, v66
	v_pk_mul_f32 v[66:67], v[172:173], v[52:53] op_sel_hi:[0,1]
	v_mul_f32_e32 v82, v64, v64
	v_max_f32_e32 v64, 0, v65
	v_max_f32_e32 v66, 0, v66
	v_max_f32_e32 v67, 0, v67
	v_mul_f32_e32 v65, v64, v64
	v_mul_f32_e32 v66, v66, v66
	v_mul_f32_e32 v67, v67, v67
	v_cvt_pk_bf16_f32 v64, v66, v67
	v_cvt_pk_bf16_f32 v65, v82, v65
	v_addc_co_u32_e32 v75, vcc, 0, v75, vcc
	v_cvt_pk_bf16_f32 v66, v78, v79
	v_cvt_pk_bf16_f32 v67, v80, v81
	global_store_dwordx4 v[74:75], v[64:67], off
	s_nop 1
	v_pk_mul_f32 v[64:65], v[170:171], v[42:43] op_sel_hi:[0,1]
	v_max_f32_e32 v64, 0, v64
	v_pk_mul_f32 v[66:67], v[170:171], v[40:41] op_sel_hi:[0,1]
	v_mul_f32_e32 v80, v64, v64
	v_max_f32_e32 v64, 0, v65
	v_max_f32_e32 v66, 0, v66
	v_mul_f32_e32 v81, v64, v64
	v_pk_mul_f32 v[64:65], v[170:171], v[46:47] op_sel_hi:[0,1]
	v_mul_f32_e32 v78, v66, v66
	v_max_f32_e32 v66, 0, v67
	v_max_f32_e32 v64, 0, v64
	v_mul_f32_e32 v79, v66, v66
	v_pk_mul_f32 v[66:67], v[170:171], v[44:45] op_sel_hi:[0,1]
	v_mul_f32_e32 v82, v64, v64
	v_max_f32_e32 v64, 0, v65
	v_max_f32_e32 v66, 0, v66
	v_max_f32_e32 v67, 0, v67
	v_mul_f32_e32 v65, v64, v64
	v_mul_f32_e32 v66, v66, v66
	v_mul_f32_e32 v67, v67, v67
	v_cvt_pk_bf16_f32 v64, v66, v67
	v_cvt_pk_bf16_f32 v65, v82, v65
	v_cvt_pk_bf16_f32 v66, v78, v79
	v_cvt_pk_bf16_f32 v67, v80, v81
	global_store_dwordx4 v[76:77], v[64:67], off offset:1024
	s_nop 1
	v_pk_mul_f32 v[64:65], v[170:171], v[26:27] op_sel_hi:[0,1]
	v_max_f32_e32 v64, 0, v64
	v_pk_mul_f32 v[66:67], v[170:171], v[24:25] op_sel_hi:[0,1]
	v_mul_f32_e32 v80, v64, v64
	v_max_f32_e32 v64, 0, v65
	v_max_f32_e32 v66, 0, v66
	v_mul_f32_e32 v81, v64, v64
	v_pk_mul_f32 v[64:65], v[170:171], v[30:31] op_sel_hi:[0,1]
	v_mul_f32_e32 v78, v66, v66
	v_max_f32_e32 v66, 0, v67
	v_max_f32_e32 v64, 0, v64
	v_mul_f32_e32 v79, v66, v66
	v_pk_mul_f32 v[66:67], v[170:171], v[28:29] op_sel_hi:[0,1]
	v_mul_f32_e32 v82, v64, v64
	v_max_f32_e32 v64, 0, v65
	v_max_f32_e32 v66, 0, v66
	v_max_f32_e32 v67, 0, v67
	v_mul_f32_e32 v65, v64, v64
	v_mul_f32_e32 v66, v66, v66
	v_mul_f32_e32 v67, v67, v67
	v_cvt_pk_bf16_f32 v64, v66, v67
	v_cvt_pk_bf16_f32 v65, v82, v65
	v_cvt_pk_bf16_f32 v66, v78, v79
	v_cvt_pk_bf16_f32 v67, v80, v81
	global_store_dwordx4 v[74:75], v[64:67], off offset:1024
	s_nop 1
	v_pk_mul_f32 v[64:65], v[168:169], v[34:35] op_sel_hi:[0,1]
	v_max_f32_e32 v64, 0, v64
	v_pk_mul_f32 v[66:67], v[168:169], v[32:33] op_sel_hi:[0,1]
	v_mul_f32_e32 v80, v64, v64
	v_max_f32_e32 v64, 0, v65
	v_max_f32_e32 v66, 0, v66
	v_mul_f32_e32 v81, v64, v64
	v_pk_mul_f32 v[64:65], v[168:169], v[38:39] op_sel_hi:[0,1]
	v_mul_f32_e32 v78, v66, v66
	v_max_f32_e32 v66, 0, v67
	v_max_f32_e32 v64, 0, v64
	v_mul_f32_e32 v79, v66, v66
	v_pk_mul_f32 v[66:67], v[168:169], v[36:37] op_sel_hi:[0,1]
	v_mul_f32_e32 v82, v64, v64
	v_max_f32_e32 v64, 0, v65
	v_max_f32_e32 v66, 0, v66
	v_max_f32_e32 v67, 0, v67
	v_mul_f32_e32 v65, v64, v64
	v_mul_f32_e32 v66, v66, v66
	v_mul_f32_e32 v67, v67, v67
	v_cvt_pk_bf16_f32 v64, v66, v67
	v_cvt_pk_bf16_f32 v65, v82, v65
	v_cvt_pk_bf16_f32 v66, v78, v79
	v_cvt_pk_bf16_f32 v67, v80, v81
	global_store_dwordx4 v[76:77], v[64:67], off offset:2048
	s_nop 1
	v_pk_mul_f32 v[64:65], v[168:169], v[18:19] op_sel_hi:[0,1]
	v_max_f32_e32 v64, 0, v64
	v_pk_mul_f32 v[66:67], v[168:169], v[16:17] op_sel_hi:[0,1]
	v_mul_f32_e32 v80, v64, v64
	v_max_f32_e32 v64, 0, v65
	v_max_f32_e32 v66, 0, v66
	v_mul_f32_e32 v81, v64, v64
	v_pk_mul_f32 v[64:65], v[168:169], v[22:23] op_sel_hi:[0,1]
	v_mul_f32_e32 v78, v66, v66
	v_max_f32_e32 v66, 0, v67
	v_max_f32_e32 v64, 0, v64
	v_mul_f32_e32 v79, v66, v66
	v_pk_mul_f32 v[66:67], v[168:169], v[20:21] op_sel_hi:[0,1]
	v_mul_f32_e32 v82, v64, v64
	v_max_f32_e32 v64, 0, v65
	v_max_f32_e32 v66, 0, v66
	v_max_f32_e32 v67, 0, v67
	v_mul_f32_e32 v65, v64, v64
	v_mul_f32_e32 v66, v66, v66
	v_mul_f32_e32 v67, v67, v67
	v_cvt_pk_bf16_f32 v64, v66, v67
	v_cvt_pk_bf16_f32 v65, v82, v65
	v_cvt_pk_bf16_f32 v66, v78, v79
	v_cvt_pk_bf16_f32 v67, v80, v81
	global_store_dwordx4 v[74:75], v[64:67], off offset:2048
	s_nop 1
	v_pk_mul_f32 v[64:65], v[166:167], v[10:11] op_sel_hi:[0,1]
	v_max_f32_e32 v64, 0, v64
	v_pk_mul_f32 v[66:67], v[166:167], v[8:9] op_sel_hi:[0,1]
	v_mul_f32_e32 v78, v64, v64
	v_max_f32_e32 v64, 0, v65
	v_max_f32_e32 v66, 0, v66
	v_mul_f32_e32 v79, v64, v64
	v_pk_mul_f32 v[64:65], v[166:167], v[14:15] op_sel_hi:[0,1]
	v_mul_f32_e32 v74, v66, v66
	v_max_f32_e32 v66, 0, v67
	v_max_f32_e32 v64, 0, v64
	v_mul_f32_e32 v75, v66, v66
	v_pk_mul_f32 v[66:67], v[166:167], v[12:13] op_sel_hi:[0,1]
	v_mul_f32_e32 v80, v64, v64
	v_max_f32_e32 v64, 0, v65
	v_max_f32_e32 v66, 0, v66
	v_max_f32_e32 v67, 0, v67
	v_mul_f32_e32 v65, v64, v64
	v_mul_f32_e32 v66, v66, v66
	v_mul_f32_e32 v67, v67, v67
	v_cvt_pk_bf16_f32 v64, v66, v67
	v_cvt_pk_bf16_f32 v65, v80, v65
	v_cvt_pk_bf16_f32 v66, v74, v75
	v_cvt_pk_bf16_f32 v67, v78, v79
	global_store_dwordx4 v[76:77], v[64:67], off offset:3072
	s_nop 1
	v_pk_mul_f32 v[64:65], v[166:167], v[2:3] op_sel_hi:[0,1]
	v_pk_mul_f32 v[66:67], v[166:167], v[0:1] op_sel_hi:[0,1]
	v_max_f32_e32 v64, 0, v64
	v_max_f32_e32 v66, 0, v66
	v_mul_f32_e32 v76, v64, v64
	v_max_f32_e32 v64, 0, v65
	v_mul_f32_e32 v74, v66, v66
	v_max_f32_e32 v66, 0, v67
	v_mul_f32_e32 v77, v64, v64
	v_pk_mul_f32 v[64:65], v[166:167], v[6:7] op_sel_hi:[0,1]
	v_mul_f32_e32 v75, v66, v66
	v_pk_mul_f32 v[66:67], v[166:167], v[4:5] op_sel_hi:[0,1]
	v_max_f32_e32 v64, 0, v64
	v_max_f32_e32 v66, 0, v66
	v_max_f32_e32 v67, 0, v67
	v_mul_f32_e32 v78, v64, v64
	v_max_f32_e32 v64, 0, v65
	v_mul_f32_e32 v66, v66, v66
	v_mul_f32_e32 v67, v67, v67
	v_mul_f32_e32 v65, v64, v64
	v_cvt_pk_bf16_f32 v64, v66, v67
	v_cvt_pk_bf16_f32 v65, v78, v65
	v_cvt_pk_bf16_f32 v66, v74, v75
	v_cvt_pk_bf16_f32 v67, v76, v77
	v_add_u32_e32 v74, 0x82c00, v164
	s_cbranch_execnz .LBB0_222
	s_branch .LBB0_221

.LBB0_292:
	s_cmp_lt_i32 s52, 8
	s_cselect_b64 s[0:1], -1, 0
	s_cmp_gt_i32 s53, 7
	s_cselect_b64 s[2:3], -1, 0
	s_and_b64 s[0:1], s[0:1], s[2:3]
	s_andn2_b64 vcc, exec, s[0:1]
	s_cbranch_vccnz .LBB0_314
	s_lshl_b32 s0, s33, 3
	v_readlane_b32 s1, v242, 1
	s_add_i32 s0, s0, s1
	s_cmpk_gt_u32 s0, 0x1fff
	v_mbcnt_lo_u32_b32 v0, -1, 0
	v_mbcnt_hi_u32_b32 v0, -1, v0
	s_cbranch_scc1 .LBB0_304
	v_lshlrev_b32_e32 v0, 3, v0
	v_and_b32_e32 v34, 0x1f8, v0
	v_lshlrev_b32_e32 v64, 2, v34
	s_waitcnt lgkmcnt(0)
	v_mov_b32_e32 v65, 0
	s_waitcnt vmcnt(0)
	v_lshl_add_u64 v[16:17], s[42:43], 0, v[64:65]
	s_mov_b64 s[4:5], 0x1000
	s_add_u32 s2, s54, 0x2000000
	s_mov_b32 s1, 0
	v_lshl_add_u64 v[24:25], v[16:17], 0, s[4:5]
	s_movk_i32 s4, 0x1000
	s_addc_u32 s3, s55, 0
	v_add_co_u32_e32 v32, vcc, s4, v16
	s_lshl_b32 s12, s84, 3
	s_lshl_b64 s[4:5], s[0:1], 12
	s_lshl_b64 s[6:7], s[0:1], 13
	s_add_u32 s6, s40, s6
	s_addc_u32 s7, s41, s7
	global_load_dwordx4 v[0:3], v64, s[42:43]
	global_load_dwordx4 v[4:7], v64, s[42:43] offset:16
	global_load_dwordx4 v[8:11], v64, s[42:43] offset:2048
	global_load_dwordx4 v[12:15], v64, s[42:43] offset:2064
	v_addc_co_u32_e32 v33, vcc, 0, v17, vcc
	v_lshlrev_b32_e32 v64, 1, v34
	s_add_u32 s4, s2, s4
	global_load_dwordx4 v[16:19], v[32:33], off
	global_load_dwordx4 v[20:23], v[24:25], off offset:16
	s_nop 0
	global_load_dwordx4 v[24:27], v[32:33], off offset:2048
	global_load_dwordx4 v[28:31], v[32:33], off offset:2064
	s_addc_u32 s5, s3, s5
	global_load_dwordx4 v[32:35], v64, s[6:7] nt
	global_load_dwordx4 v[36:39], v64, s[6:7] offset:1024 nt
	global_load_dwordx4 v[40:43], v64, s[4:5] nt
	global_load_dwordx4 v[44:47], v64, s[4:5] offset:1024 nt
	global_load_dwordx4 v[48:51], v64, s[6:7] offset:2048 nt
	global_load_dwordx4 v[52:55], v64, s[6:7] offset:3072 nt
	global_load_dwordx4 v[56:59], v64, s[4:5] offset:2048 nt
	global_load_dwordx4 v[60:63], v64, s[4:5] offset:3072 nt
	v_mbcnt_lo_u32_b32 v66, -1, 0
	v_mbcnt_hi_u32_b32 v66, -1, v66
	v_and_b32_e32 v67, 64, v66
	v_add_u32_e32 v67, 64, v67
	v_xor_b32_e32 v68, 32, v66
	v_cmp_lt_i32_e32 vcc, v68, v67
	s_cmp_lg_u64 s[48:49], 0
	v_lshl_add_u64 v[96:97], s[40:41], 0, v[64:65]
	v_cndmask_b32_e32 v68, v66, v68, vcc
	v_lshlrev_b32_e32 v108, 2, v68
	v_xor_b32_e32 v68, 16, v66
	v_cmp_lt_i32_e32 vcc, v68, v67
	v_lshl_add_u64 v[98:99], s[2:3], 0, v[64:65]
	s_cselect_b64 s[2:3], -1, 0
	v_cndmask_b32_e32 v68, v66, v68, vcc
	v_lshlrev_b32_e32 v109, 2, v68
	v_xor_b32_e32 v68, 8, v66
	v_cmp_lt_i32_e32 vcc, v68, v67
	v_lshl_add_u64 v[100:101], s[54:55], 0, v[64:65]
	s_lshl_b32 s13, s84, 4
	v_cndmask_b32_e32 v68, v66, v68, vcc
	v_lshlrev_b32_e32 v110, 2, v68
	v_xor_b32_e32 v68, 4, v66
	v_cmp_lt_i32_e32 vcc, v68, v67
	v_mov_b32_e32 v114, 0x358637bd
	s_mov_b32 s14, 0x800000
	v_cndmask_b32_e32 v68, v66, v68, vcc
	v_lshlrev_b32_e32 v111, 2, v68
	v_xor_b32_e32 v68, 2, v66
	v_cmp_lt_i32_e32 vcc, v68, v67
	s_nop 1
	v_cndmask_b32_e32 v68, v66, v68, vcc
	v_lshlrev_b32_e32 v112, 2, v68
	v_xor_b32_e32 v68, 1, v66
	v_cmp_lt_i32_e32 vcc, v68, v67
	s_nop 1
	v_cndmask_b32_e32 v66, v66, v68, vcc
	v_lshlrev_b32_e32 v113, 2, v66
	s_waitcnt vmcnt(0)
	s_branch .LBB0_296

.LBB0_296:
	s_waitcnt vmcnt(13)
	v_and_b32_e32 v149, 0xffff0000, v40
	v_lshlrev_b32_e32 v143, 16, v40
	v_mul_f32_e32 v122, v149, v149
	v_lshlrev_b32_e32 v150, 16, v41
	v_fmac_f32_e32 v122, v143, v143
	v_and_b32_e32 v151, 0xffff0000, v41
	v_fmac_f32_e32 v122, v150, v150
	v_lshlrev_b32_e32 v152, 16, v42
	v_fmac_f32_e32 v122, v151, v151
	v_and_b32_e32 v153, 0xffff0000, v42
	v_fmac_f32_e32 v122, v152, v152
	v_lshlrev_b32_e32 v154, 16, v43
	v_fmac_f32_e32 v122, v153, v153
	v_and_b32_e32 v155, 0xffff0000, v43
	v_fmac_f32_e32 v122, v154, v154
	v_fmac_f32_e32 v122, v155, v155
	s_waitcnt vmcnt(12)
	v_lshlrev_b32_e32 v156, 16, v44
	v_and_b32_e32 v157, 0xffff0000, v44
	v_fmac_f32_e32 v122, v156, v156
	v_lshlrev_b32_e32 v158, 16, v45
	v_fmac_f32_e32 v122, v157, v157
	v_and_b32_e32 v159, 0xffff0000, v45
	v_fmac_f32_e32 v122, v158, v158
	v_lshlrev_b32_e32 v160, 16, v46
	v_fmac_f32_e32 v122, v159, v159
	v_and_b32_e32 v161, 0xffff0000, v46
	v_fmac_f32_e32 v122, v160, v160
	v_lshlrev_b32_e32 v162, 16, v47
	v_fmac_f32_e32 v122, v161, v161
	v_and_b32_e32 v163, 0xffff0000, v47
	v_fmac_f32_e32 v122, v162, v162
	v_fmac_f32_e32 v122, v163, v163
	s_waitcnt vmcnt(9)
	v_lshlrev_b32_e32 v164, 16, v56
	v_and_b32_e32 v165, 0xffff0000, v56
	v_fmac_f32_e32 v122, v164, v164
	s_add_i32 s6, s0, s12
	s_mov_b32 s7, s1
	v_lshlrev_b32_e32 v166, 16, v57
	v_fmac_f32_e32 v122, v165, v165
	s_lshl_b64 s[8:9], s[6:7], 13
	v_and_b32_e32 v167, 0xffff0000, v57
	v_fmac_f32_e32 v122, v166, v166
	s_lshl_b64 s[4:5], s[6:7], 12
	v_lshl_add_u64 v[102:103], v[96:97], 0, s[8:9]
	v_lshlrev_b32_e32 v168, 16, v58
	v_fmac_f32_e32 v122, v167, v167
	v_lshl_add_u64 v[104:105], v[98:99], 0, s[4:5]
	global_load_dwordx4 v[76:79], v[102:103], off nt
	global_load_dwordx4 v[72:75], v[102:103], off offset:1024 nt
	global_load_dwordx4 v[92:95], v[104:105], off nt
	global_load_dwordx4 v[88:91], v[104:105], off offset:1024 nt
	global_load_dwordx4 v[68:71], v[102:103], off offset:2048 nt
	global_load_dwordx4 v[64:67], v[102:103], off offset:3072 nt
	global_load_dwordx4 v[84:87], v[104:105], off offset:2048 nt
	global_load_dwordx4 v[80:83], v[104:105], off offset:3072 nt
	v_and_b32_e32 v169, 0xffff0000, v58
	v_fmac_f32_e32 v122, v168, v168
	v_lshlrev_b32_e32 v170, 16, v59
	v_fmac_f32_e32 v122, v169, v169
	v_and_b32_e32 v171, 0xffff0000, v59
	v_fmac_f32_e32 v122, v170, v170
	v_fmac_f32_e32 v122, v171, v171
	s_waitcnt vmcnt(16)
	v_lshlrev_b32_e32 v172, 16, v60
	v_and_b32_e32 v173, 0xffff0000, v60
	v_fmac_f32_e32 v122, v172, v172
	v_lshlrev_b32_e32 v174, 16, v61
	v_fmac_f32_e32 v122, v173, v173
	v_and_b32_e32 v175, 0xffff0000, v61
	v_fmac_f32_e32 v122, v174, v174
	v_and_b32_e32 v145, 0xffff0000, v62
	v_lshlrev_b32_e32 v144, 16, v62
	v_fmac_f32_e32 v122, v175, v175
	v_pk_mul_f32 v[120:121], v[144:145], v[144:145]
	v_and_b32_e32 v105, 0xffff0000, v63
	v_lshlrev_b32_e32 v104, 16, v63
	v_add_f32_e32 v120, v120, v122
	v_pk_mul_f32 v[106:107], v[104:105], v[104:105]
	v_add_f32_e32 v120, v121, v120
	v_add_f32_e32 v106, v106, v120
	v_add_f32_e32 v106, v107, v106
	ds_bpermute_b32 v107, v108, v106
	v_lshlrev_b32_e32 v115, 16, v32
	v_and_b32_e32 v116, 0xffff0000, v32
	v_lshlrev_b32_e32 v117, 16, v33
	v_and_b32_e32 v118, 0xffff0000, v33
	s_waitcnt lgkmcnt(0)
	v_add_f32_e32 v106, v106, v107
	ds_bpermute_b32 v107, v109, v106
	v_lshlrev_b32_e32 v119, 16, v34
	v_and_b32_e32 v134, 0xffff0000, v34
	v_lshlrev_b32_e32 v135, 16, v35
	v_and_b32_e32 v136, 0xffff0000, v35
	s_waitcnt lgkmcnt(0)
	v_add_f32_e32 v106, v106, v107
	ds_bpermute_b32 v107, v110, v106
	v_lshlrev_b32_e32 v132, 16, v36
	v_and_b32_e32 v141, 0xffff0000, v36
	v_lshlrev_b32_e32 v137, 16, v37
	v_and_b32_e32 v138, 0xffff0000, v37
	s_waitcnt lgkmcnt(0)
	v_add_f32_e32 v106, v106, v107
	ds_bpermute_b32 v107, v111, v106
	v_lshlrev_b32_e32 v133, 16, v38
	v_and_b32_e32 v142, 0xffff0000, v38
	v_lshlrev_b32_e32 v139, 16, v39
	v_and_b32_e32 v140, 0xffff0000, v39
	s_waitcnt lgkmcnt(0)
	v_add_f32_e32 v106, v106, v107
	ds_bpermute_b32 v107, v112, v106
	v_lshlrev_b32_e32 v124, 16, v48
	v_and_b32_e32 v130, 0xffff0000, v48
	v_lshlrev_b32_e32 v126, 16, v49
	v_and_b32_e32 v127, 0xffff0000, v49
	s_waitcnt lgkmcnt(0)
	v_add_f32_e32 v106, v106, v107
	ds_bpermute_b32 v107, v113, v106
	v_lshlrev_b32_e32 v125, 16, v50
	v_and_b32_e32 v131, 0xffff0000, v50
	v_lshlrev_b32_e32 v128, 16, v51
	v_and_b32_e32 v129, 0xffff0000, v51
	s_waitcnt lgkmcnt(0)
	v_add_f32_e32 v106, v106, v107
	v_fmamk_f32 v106, v106, 0x3a000000, v114
	v_mul_f32_e32 v107, 0x4b800000, v106
	v_cmp_gt_f32_e32 vcc, s14, v106
	v_lshlrev_b32_e32 v120, 16, v52
	v_and_b32_e32 v123, 0xffff0000, v52
	v_cndmask_b32_e32 v106, v106, v107, vcc
	v_rsq_f32_e32 v148, v106
	v_lshlrev_b32_e32 v121, 16, v53
	v_and_b32_e32 v122, 0xffff0000, v53
	v_and_b32_e32 v147, 0xffff0000, v55
	v_mul_f32_e32 v176, 0x45800000, v148
	v_cndmask_b32_e32 v148, v148, v176, vcc
	v_mul_f32_e32 v143, v148, v143
	v_fmac_f32_e32 v115, v0, v143
	v_mul_f32_e32 v143, v148, v149
	v_fmac_f32_e32 v116, v1, v143
	v_mul_f32_e32 v143, v148, v150
	v_fmac_f32_e32 v117, v2, v143
	v_mul_f32_e32 v143, v148, v151
	v_fmac_f32_e32 v118, v3, v143
	v_mul_f32_e32 v143, v148, v152
	v_fmac_f32_e32 v119, v4, v143
	v_mul_f32_e32 v143, v148, v153
	v_fmac_f32_e32 v134, v5, v143
	v_mul_f32_e32 v143, v148, v154
	v_fmac_f32_e32 v135, v6, v143
	v_mul_f32_e32 v143, v148, v155
	v_fmac_f32_e32 v136, v7, v143
	v_mul_f32_e32 v143, v148, v156
	v_fmac_f32_e32 v132, v8, v143
	v_mul_f32_e32 v143, v148, v157
	v_fmac_f32_e32 v141, v9, v143
	v_mul_f32_e32 v143, v148, v158
	v_fmac_f32_e32 v137, v10, v143
	v_mul_f32_e32 v143, v148, v159
	v_fmac_f32_e32 v138, v11, v143
	v_mul_f32_e32 v143, v148, v160
	v_fmac_f32_e32 v133, v12, v143
	v_mul_f32_e32 v143, v148, v161
	v_fmac_f32_e32 v142, v13, v143
	v_mul_f32_e32 v143, v148, v162
	v_fmac_f32_e32 v139, v14, v143
	v_mul_f32_e32 v143, v148, v163
	v_fmac_f32_e32 v140, v15, v143
	v_mul_f32_e32 v143, v148, v164
	v_fmac_f32_e32 v124, v16, v143
	v_mul_f32_e32 v143, v148, v165
	v_fmac_f32_e32 v130, v17, v143
	v_mul_f32_e32 v143, v148, v166
	v_fmac_f32_e32 v126, v18, v143
	v_mul_f32_e32 v143, v148, v167
	v_fmac_f32_e32 v127, v19, v143
	v_mul_f32_e32 v143, v148, v168
	v_fmac_f32_e32 v125, v20, v143
	v_mul_f32_e32 v143, v148, v169
	v_fmac_f32_e32 v131, v21, v143
	v_mul_f32_e32 v143, v148, v170
	v_fmac_f32_e32 v128, v22, v143
	v_mul_f32_e32 v143, v148, v171
	v_fmac_f32_e32 v129, v23, v143
	v_mul_f32_e32 v143, v148, v172
	v_fmac_f32_e32 v120, v24, v143
	v_mul_f32_e32 v143, v148, v173
	v_fmac_f32_e32 v123, v25, v143
	v_mul_f32_e32 v143, v148, v174
	v_lshlrev_b32_e32 v146, 16, v55
	v_and_b32_e32 v107, 0xffff0000, v54
	v_lshlrev_b32_e32 v106, 16, v54
	v_fmac_f32_e32 v121, v26, v143
	v_mul_f32_e32 v143, v148, v175
	v_pk_mul_f32 v[144:145], v[148:149], v[144:145] op_sel_hi:[0,1]
	v_pk_mul_f32 v[104:105], v[148:149], v[104:105] op_sel_hi:[0,1]
	v_fmac_f32_e32 v122, v27, v143
	v_pk_fma_f32 v[106:107], v[28:29], v[144:145], v[106:107]
	v_pk_fma_f32 v[104:105], v[30:31], v[104:105], v[146:147]
	s_and_b64 vcc, exec, s[2:3]
	s_cbranch_vccz .LBB0_303
	s_lshl_b64 s[10:11], s[0:1], 13
	v_cvt_pk_bf16_f32 v144, v115, v116
	v_cvt_pk_bf16_f32 v145, v117, v118
	v_cvt_pk_bf16_f32 v146, v119, v134
	v_cvt_pk_bf16_f32 v147, v135, v136
	v_lshl_add_u64 v[148:149], v[96:97], 0, s[10:11]
	global_store_dwordx4 v[148:149], v[144:147], off nt
	s_lshl_b64 s[8:9], s[0:1], 12
	s_nop 0
	v_cvt_pk_bf16_f32 v144, v132, v141
	v_cvt_pk_bf16_f32 v145, v137, v138
	v_cvt_pk_bf16_f32 v146, v133, v142
	v_cvt_pk_bf16_f32 v147, v139, v140
	global_store_dwordx4 v[148:149], v[144:147], off offset:1024 nt
	s_nop 1
	v_cvt_pk_bf16_f32 v144, v124, v130
	v_cvt_pk_bf16_f32 v145, v126, v127
	v_cvt_pk_bf16_f32 v146, v125, v131
	v_cvt_pk_bf16_f32 v147, v128, v129
	global_store_dwordx4 v[148:149], v[144:147], off offset:2048 nt
	s_nop 1
	v_cvt_pk_bf16_f32 v144, v120, v123
	v_cvt_pk_bf16_f32 v145, v121, v122
	v_cvt_pk_bf16_f32 v146, v106, v107
	v_cvt_pk_bf16_f32 v147, v104, v105
	global_store_dwordx4 v[148:149], v[144:147], off offset:3072 nt
	s_cbranch_execnz .LBB0_299

.LBB0_301:
	s_waitcnt vmcnt(21)
	v_and_b32_e32 v115, 0xffff0000, v92
	v_lshlrev_b32_e32 v107, 16, v92
	v_mul_f32_e32 v92, v115, v115
	v_lshlrev_b32_e32 v119, 16, v93
	v_fmac_f32_e32 v92, v107, v107
	v_and_b32_e32 v93, 0xffff0000, v93
	v_fmac_f32_e32 v92, v119, v119
	v_lshlrev_b32_e32 v120, 16, v94
	v_fmac_f32_e32 v92, v93, v93
	v_and_b32_e32 v121, 0xffff0000, v94
	v_fmac_f32_e32 v92, v120, v120
	v_lshlrev_b32_e32 v122, 16, v95
	v_fmac_f32_e32 v92, v121, v121
	v_and_b32_e32 v123, 0xffff0000, v95
	v_fmac_f32_e32 v92, v122, v122
	v_fmac_f32_e32 v92, v123, v123
	s_waitcnt vmcnt(20)
	v_lshlrev_b32_e32 v124, 16, v88
	v_and_b32_e32 v125, 0xffff0000, v88
	v_fmac_f32_e32 v92, v124, v124
	v_lshlrev_b32_e32 v126, 16, v89
	v_fmac_f32_e32 v92, v125, v125
	v_and_b32_e32 v127, 0xffff0000, v89
	v_fmac_f32_e32 v92, v126, v126
	v_lshlrev_b32_e32 v128, 16, v90
	v_fmac_f32_e32 v92, v127, v127
	v_and_b32_e32 v129, 0xffff0000, v90
	v_fmac_f32_e32 v92, v128, v128
	v_lshlrev_b32_e32 v130, 16, v91
	v_fmac_f32_e32 v92, v129, v129
	v_and_b32_e32 v131, 0xffff0000, v91
	v_fmac_f32_e32 v92, v130, v130
	v_fmac_f32_e32 v92, v131, v131
	s_waitcnt vmcnt(17)
	v_lshlrev_b32_e32 v132, 16, v84
	v_and_b32_e32 v133, 0xffff0000, v84
	v_fmac_f32_e32 v92, v132, v132
	v_lshlrev_b32_e32 v134, 16, v85
	v_fmac_f32_e32 v92, v133, v133
	v_and_b32_e32 v135, 0xffff0000, v85
	v_fmac_f32_e32 v92, v134, v134
	v_lshlrev_b32_e32 v136, 16, v86
	v_fmac_f32_e32 v92, v135, v135
	v_and_b32_e32 v137, 0xffff0000, v86
	v_fmac_f32_e32 v92, v136, v136
	v_lshlrev_b32_e32 v138, 16, v87
	v_fmac_f32_e32 v92, v137, v137
	v_and_b32_e32 v139, 0xffff0000, v87
	v_fmac_f32_e32 v92, v138, v138
	v_fmac_f32_e32 v92, v139, v139
	s_waitcnt vmcnt(16)
	v_lshlrev_b32_e32 v140, 16, v80
	v_and_b32_e32 v141, 0xffff0000, v80
	v_fmac_f32_e32 v92, v140, v140
	v_lshlrev_b32_e32 v142, 16, v81
	v_fmac_f32_e32 v92, v141, v141
	v_and_b32_e32 v143, 0xffff0000, v81
	v_fmac_f32_e32 v92, v142, v142
	v_and_b32_e32 v117, 0xffff0000, v82
	v_lshlrev_b32_e32 v116, 16, v82
	v_fmac_f32_e32 v92, v143, v143
	v_and_b32_e32 v95, 0xffff0000, v83
	v_lshlrev_b32_e32 v94, 16, v83
	v_pk_mul_f32 v[82:83], v[116:117], v[116:117]
	v_pk_mul_f32 v[80:81], v[94:95], v[94:95]
	v_add_f32_e32 v82, v82, v92
	v_add_f32_e32 v82, v83, v82
	v_add_f32_e32 v80, v80, v82
	v_add_f32_e32 v80, v81, v80
	ds_bpermute_b32 v81, v108, v80
	v_lshlrev_b32_e32 v106, 16, v78
	v_and_b32_e32 v84, 0xffff0000, v78
	v_lshlrev_b32_e32 v85, 16, v79
	v_and_b32_e32 v86, 0xffff0000, v79
	s_waitcnt lgkmcnt(0)
	v_add_f32_e32 v78, v80, v81
	ds_bpermute_b32 v79, v109, v78
	v_lshlrev_b32_e32 v87, 16, v73
	v_and_b32_e32 v88, 0xffff0000, v73
	v_lshlrev_b32_e32 v83, 16, v74
	v_and_b32_e32 v92, 0xffff0000, v74
	s_waitcnt lgkmcnt(0)
	v_add_f32_e32 v73, v78, v79
	ds_bpermute_b32 v78, v110, v73
	v_lshlrev_b32_e32 v89, 16, v75
	v_and_b32_e32 v90, 0xffff0000, v75
	v_lshlrev_b32_e32 v74, 16, v69
	v_and_b32_e32 v75, 0xffff0000, v69
	s_waitcnt lgkmcnt(0)
	v_add_f32_e32 v78, v73, v78
	ds_bpermute_b32 v79, v111, v78
	v_lshlrev_b32_e32 v82, 16, v72
	v_and_b32_e32 v91, 0xffff0000, v72
	v_lshlrev_b32_e32 v72, 16, v68
	v_and_b32_e32 v80, 0xffff0000, v68
	s_waitcnt lgkmcnt(0)
	v_add_f32_e32 v69, v78, v79
	ds_bpermute_b32 v118, v112, v69
	v_lshlrev_b32_e32 v78, 16, v71
	v_and_b32_e32 v79, 0xffff0000, v71
	v_lshlrev_b32_e32 v68, 16, v64
	v_and_b32_e32 v71, 0xffff0000, v64
	s_waitcnt lgkmcnt(0)
	v_add_f32_e32 v118, v69, v118
	ds_bpermute_b32 v144, v113, v118
	v_lshlrev_b32_e32 v105, 16, v77
	v_and_b32_e32 v77, 0xffff0000, v77
	v_lshlrev_b32_e32 v73, 16, v70
	v_and_b32_e32 v81, 0xffff0000, v70
	s_waitcnt lgkmcnt(0)
	v_add_f32_e32 v64, v118, v144
	v_fmamk_f32 v64, v64, 0x3a000000, v114
	v_mul_f32_e32 v118, 0x4b800000, v64
	v_cmp_gt_f32_e32 vcc, s14, v64
	v_lshlrev_b32_e32 v104, 16, v76
	v_and_b32_e32 v76, 0xffff0000, v76
	v_cndmask_b32_e32 v64, v64, v118, vcc
	v_rsq_f32_e32 v118, v64
	v_lshlrev_b32_e32 v69, 16, v65
	v_and_b32_e32 v70, 0xffff0000, v65
	v_and_b32_e32 v65, 0xffff0000, v67
	v_mul_f32_e32 v144, 0x45800000, v118
	v_cndmask_b32_e32 v118, v118, v144, vcc
	v_mul_f32_e32 v93, v118, v93
	v_fmac_f32_e32 v77, v3, v93
	v_mul_f32_e32 v93, v118, v120
	v_fmac_f32_e32 v106, v4, v93
	v_mul_f32_e32 v93, v118, v121
	v_fmac_f32_e32 v84, v5, v93
	v_mul_f32_e32 v93, v118, v122
	v_fmac_f32_e32 v85, v6, v93
	v_mul_f32_e32 v93, v118, v123
	v_fmac_f32_e32 v86, v7, v93
	v_mul_f32_e32 v93, v118, v124
	v_fmac_f32_e32 v82, v8, v93
	v_mul_f32_e32 v93, v118, v125
	v_fmac_f32_e32 v91, v9, v93
	v_mul_f32_e32 v93, v118, v126
	v_fmac_f32_e32 v87, v10, v93
	v_mul_f32_e32 v93, v118, v127
	v_fmac_f32_e32 v88, v11, v93
	v_mul_f32_e32 v93, v118, v128
	v_fmac_f32_e32 v83, v12, v93
	v_mul_f32_e32 v93, v118, v129
	v_fmac_f32_e32 v92, v13, v93
	v_mul_f32_e32 v93, v118, v130
	v_fmac_f32_e32 v89, v14, v93
	v_mul_f32_e32 v93, v118, v131
	v_fmac_f32_e32 v90, v15, v93
	v_mul_f32_e32 v93, v118, v132
	v_fmac_f32_e32 v72, v16, v93
	v_mul_f32_e32 v93, v118, v133
	v_fmac_f32_e32 v80, v17, v93
	v_mul_f32_e32 v93, v118, v134
	v_fmac_f32_e32 v74, v18, v93
	v_mul_f32_e32 v93, v118, v135
	v_fmac_f32_e32 v75, v19, v93
	v_mul_f32_e32 v93, v118, v136
	v_fmac_f32_e32 v73, v20, v93
	v_mul_f32_e32 v93, v118, v137
	v_fmac_f32_e32 v81, v21, v93
	v_mul_f32_e32 v93, v118, v138
	v_fmac_f32_e32 v78, v22, v93
	v_mul_f32_e32 v93, v118, v139
	v_fmac_f32_e32 v79, v23, v93
	v_mul_f32_e32 v93, v118, v140
	v_mul_f32_e32 v107, v118, v107
	v_fmac_f32_e32 v68, v24, v93
	v_mul_f32_e32 v93, v118, v141
	v_fmac_f32_e32 v104, v0, v107
	v_mul_f32_e32 v107, v118, v115
	v_fmac_f32_e32 v71, v25, v93
	v_mul_f32_e32 v93, v118, v142
	v_lshlrev_b32_e32 v64, 16, v67
	v_and_b32_e32 v67, 0xffff0000, v66
	v_lshlrev_b32_e32 v66, 16, v66
	v_fmac_f32_e32 v76, v1, v107
	v_mul_f32_e32 v107, v118, v119
	v_fmac_f32_e32 v69, v26, v93
	v_mul_f32_e32 v93, v118, v143
	v_pk_mul_f32 v[116:117], v[118:119], v[116:117] op_sel_hi:[0,1]
	v_pk_mul_f32 v[94:95], v[118:119], v[94:95] op_sel_hi:[0,1]
	v_fmac_f32_e32 v105, v2, v107
	v_fmac_f32_e32 v70, v27, v93
	v_pk_fma_f32 v[66:67], v[28:29], v[116:117], v[66:67]
	v_pk_fma_f32 v[64:65], v[30:31], v[94:95], v[64:65]
	s_and_b64 vcc, exec, s[2:3]
	s_cbranch_vccz .LBB0_295
	v_cvt_pk_bf16_f32 v116, v104, v76
	v_cvt_pk_bf16_f32 v117, v105, v77
	v_cvt_pk_bf16_f32 v118, v106, v84
	v_cvt_pk_bf16_f32 v119, v85, v86
	global_store_dwordx4 v[102:103], v[116:119], off nt
	s_nop 1
	v_cvt_pk_bf16_f32 v116, v82, v91
	v_cvt_pk_bf16_f32 v117, v87, v88
	v_cvt_pk_bf16_f32 v118, v83, v92
	v_cvt_pk_bf16_f32 v119, v89, v90
	global_store_dwordx4 v[102:103], v[116:119], off offset:1024 nt
	s_nop 1
	v_cvt_pk_bf16_f32 v116, v72, v80
	v_cvt_pk_bf16_f32 v117, v74, v75
	v_cvt_pk_bf16_f32 v118, v73, v81
	v_cvt_pk_bf16_f32 v119, v78, v79
	global_store_dwordx4 v[102:103], v[116:119], off offset:2048 nt
	s_nop 1
	v_cvt_pk_bf16_f32 v116, v68, v71
	v_cvt_pk_bf16_f32 v117, v69, v70
	v_cvt_pk_bf16_f32 v118, v66, v67
	v_cvt_pk_bf16_f32 v119, v64, v65
	global_store_dwordx4 v[102:103], v[116:119], off offset:3072 nt
	s_branch .LBB0_295
.Lr7_last:
	s_waitcnt vmcnt(0)
	s_branch .LBB0_301
.LBB0_303:
	s_branch .LBB0_298

.LBB0_481:
	s_cmp_lt_i32 s52, 12
	s_cselect_b64 s[0:1], -1, 0
	s_cmp_gt_i32 s53, 11
	s_cselect_b64 s[2:3], -1, 0
	s_and_b64 s[0:1], s[0:1], s[2:3]
	s_andn2_b64 vcc, exec, s[0:1]
	s_cbranch_vccnz .LBB0_505
	s_lshl_b32 s0, s33, 3
	v_readlane_b32 s1, v242, 1
	s_waitcnt lgkmcnt(0)
	s_add_i32 s6, s0, s1
	s_cmpk_gt_u32 s6, 0x1fff
	v_mbcnt_lo_u32_b32 v0, -1, 0
	v_mbcnt_hi_u32_b32 v0, -1, v0
	s_cbranch_scc1 .LBB0_495
	v_and_b32_e32 v64, 63, v0
	s_waitcnt vmcnt(0)
	v_lshlrev_b32_e32 v96, 5, v64
	v_mov_b32_e32 v97, 0
	v_lshl_add_u64 v[24:25], s[38:39], 0, v[96:97]
	s_mov_b64 s[2:3], 0x2000
	s_mov_b32 s5, 0
	v_lshl_add_u64 v[16:17], v[24:25], 0, s[2:3]
	s_mov_b64 s[2:3], 0x3000
	s_add_u32 s0, s54, 0x4000000
	v_lshl_add_u64 v[26:27], v[24:25], 0, s[2:3]
	s_mov_b64 s[2:3], 0x3800
	s_mov_b32 s7, s5
	s_addc_u32 s1, s55, 0
	v_add_co_u32_e32 v18, vcc, 0x2000, v24
	v_lshl_add_u64 v[34:35], v[24:25], 0, s[2:3]
	s_lshl_b32 s10, s84, 3
	s_lshl_b64 s[2:3], s[6:7], 12
	s_lshl_b64 s[8:9], s[6:7], 13
	v_addc_co_u32_e32 v19, vcc, 0, v25, vcc
	s_add_u32 s8, s40, s8
	v_add_co_u32_e32 v32, vcc, 0x3000, v24
	s_addc_u32 s9, s41, s9
	s_nop 0
	v_addc_co_u32_e32 v33, vcc, 0, v25, vcc
	v_lshlrev_b32_e32 v96, 4, v64
	s_add_u32 s2, s0, s2
	global_load_dwordx4 v[0:3], v[16:17], off offset:16
	global_load_dwordx4 v[4:7], v[16:17], off offset:2048
	global_load_dwordx4 v[8:11], v[18:19], off
	global_load_dwordx4 v[12:15], v[16:17], off offset:2064
	s_nop 0
	global_load_dwordx4 v[16:19], v[32:33], off
	global_load_dwordx4 v[20:23], v[26:27], off offset:16
	s_nop 0
	global_load_dwordx4 v[24:27], v[32:33], off offset:2048
	global_load_dwordx4 v[28:31], v[34:35], off offset:16
	s_addc_u32 s3, s1, s3
	global_load_dwordx4 v[32:35], v96, s[8:9] nt
	global_load_dwordx4 v[36:39], v96, s[8:9] offset:1024 nt
	global_load_dwordx4 v[40:43], v96, s[2:3] nt
	global_load_dwordx4 v[44:47], v96, s[2:3] offset:1024 nt
	global_load_dwordx4 v[48:51], v96, s[8:9] offset:2048 nt
	global_load_dwordx4 v[52:55], v96, s[8:9] offset:3072 nt
	global_load_dwordx4 v[56:59], v96, s[2:3] offset:2048 nt
	global_load_dwordx4 v[60:63], v96, s[2:3] offset:3072 nt
	v_lshl_add_u64 v[100:101], s[0:1], 0, v[96:97]
	v_cmp_eq_u32_e64 s[0:1], 0, v64
	v_mbcnt_lo_u32_b32 v64, -1, 0
	v_mbcnt_hi_u32_b32 v64, -1, v64
	v_and_b32_e32 v65, 64, v64
	v_add_u32_e32 v65, 64, v65
	v_xor_b32_e32 v66, 32, v64
	v_cmp_lt_i32_e32 vcc, v66, v65
	v_lshl_add_u64 v[98:99], s[40:41], 0, v[96:97]
	s_cmp_lg_u64 s[48:49], 0
	v_cndmask_b32_e32 v66, v64, v66, vcc
	v_lshlrev_b32_e32 v96, 2, v66
	v_xor_b32_e32 v66, 16, v64
	v_cmp_lt_i32_e32 vcc, v66, v65
	s_cselect_b64 s[2:3], -1, 0
	s_lshl_b32 s11, s84, 4
	v_cndmask_b32_e32 v66, v64, v66, vcc
	v_lshlrev_b32_e32 v104, 2, v66
	v_xor_b32_e32 v66, 8, v64
	v_cmp_lt_i32_e32 vcc, v66, v65
	v_mov_b32_e32 v109, 0x358637bd
	s_mov_b32 s12, 0x800000
	v_cndmask_b32_e32 v66, v64, v66, vcc
	v_lshlrev_b32_e32 v105, 2, v66
	v_xor_b32_e32 v66, 4, v64
	v_cmp_lt_i32_e32 vcc, v66, v65
	s_nop 1
	v_cndmask_b32_e32 v66, v64, v66, vcc
	v_lshlrev_b32_e32 v106, 2, v66
	v_xor_b32_e32 v66, 2, v64
	v_cmp_lt_i32_e32 vcc, v66, v65
	s_nop 1
	v_cndmask_b32_e32 v66, v64, v66, vcc
	v_lshlrev_b32_e32 v107, 2, v66
	v_xor_b32_e32 v66, 1, v64
	v_cmp_lt_i32_e32 vcc, v66, v65
	s_nop 1
	v_cndmask_b32_e32 v64, v64, v66, vcc
	v_lshlrev_b32_e32 v108, 2, v64
	v_cndmask_b32_e64 v64, 0, 1, s[2:3]
	v_cmp_ne_u32_e64 s[2:3], 1, v64
	s_waitcnt vmcnt(0)
	s_branch .LBB0_485

.LBB0_485:
	s_waitcnt vmcnt(10)
	v_and_b32_e32 v147, 0xffff0000, v40
	v_lshlrev_b32_e32 v146, 16, v40
	v_mul_f32_e32 v115, v147, v147
	v_lshlrev_b32_e32 v148, 16, v41
	v_fmac_f32_e32 v115, v146, v146
	v_and_b32_e32 v149, 0xffff0000, v41
	v_fmac_f32_e32 v115, v148, v148
	v_lshlrev_b32_e32 v150, 16, v42
	v_fmac_f32_e32 v115, v149, v149
	v_and_b32_e32 v151, 0xffff0000, v42
	v_fmac_f32_e32 v115, v150, v150
	v_lshlrev_b32_e32 v152, 16, v43
	v_fmac_f32_e32 v115, v151, v151
	v_and_b32_e32 v153, 0xffff0000, v43
	v_fmac_f32_e32 v115, v152, v152
	v_fmac_f32_e32 v115, v153, v153
	s_waitcnt vmcnt(9)
	v_lshlrev_b32_e32 v154, 16, v44
	v_and_b32_e32 v155, 0xffff0000, v44
	v_fmac_f32_e32 v115, v154, v154
	v_lshlrev_b32_e32 v156, 16, v45
	v_fmac_f32_e32 v115, v155, v155
	v_and_b32_e32 v157, 0xffff0000, v45
	v_fmac_f32_e32 v115, v156, v156
	v_lshlrev_b32_e32 v158, 16, v46
	v_fmac_f32_e32 v115, v157, v157
	v_and_b32_e32 v159, 0xffff0000, v46
	v_fmac_f32_e32 v115, v158, v158
	v_lshlrev_b32_e32 v160, 16, v47
	v_fmac_f32_e32 v115, v159, v159
	v_and_b32_e32 v161, 0xffff0000, v47
	v_fmac_f32_e32 v115, v160, v160
	v_fmac_f32_e32 v115, v161, v161
	s_waitcnt vmcnt(6)
	v_lshlrev_b32_e32 v162, 16, v56
	v_and_b32_e32 v163, 0xffff0000, v56
	v_fmac_f32_e32 v115, v162, v162
	s_add_i32 s4, s6, s10
	v_lshlrev_b32_e32 v164, 16, v57
	v_fmac_f32_e32 v115, v163, v163
	s_lshl_b64 s[14:15], s[4:5], 13
	v_and_b32_e32 v165, 0xffff0000, v57
	v_fmac_f32_e32 v115, v164, v164
	s_lshl_b64 s[8:9], s[4:5], 12
	v_lshl_add_u64 v[102:103], v[98:99], 0, s[14:15]
	v_lshlrev_b32_e32 v166, 16, v58
	v_fmac_f32_e32 v115, v165, v165
	v_lshl_add_u64 v[110:111], v[100:101], 0, s[8:9]
	global_load_dwordx4 v[76:79], v[102:103], off nt
	global_load_dwordx4 v[72:75], v[102:103], off offset:1024 nt
	global_load_dwordx4 v[92:95], v[110:111], off nt
	global_load_dwordx4 v[88:91], v[110:111], off offset:1024 nt
	global_load_dwordx4 v[68:71], v[102:103], off offset:2048 nt
	s_waitcnt lgkmcnt(0)
	global_load_dwordx4 v[64:67], v[102:103], off offset:3072 nt
	global_load_dwordx4 v[84:87], v[110:111], off offset:2048 nt
	global_load_dwordx4 v[80:83], v[110:111], off offset:3072 nt
	v_and_b32_e32 v167, 0xffff0000, v58
	v_fmac_f32_e32 v115, v166, v166
	v_lshlrev_b32_e32 v168, 16, v59
	v_fmac_f32_e32 v115, v167, v167
	v_and_b32_e32 v169, 0xffff0000, v59
	v_fmac_f32_e32 v115, v168, v168
	v_fmac_f32_e32 v115, v169, v169
	s_waitcnt vmcnt(13)
	v_lshlrev_b32_e32 v170, 16, v60
	v_and_b32_e32 v171, 0xffff0000, v60
	v_fmac_f32_e32 v115, v170, v170
	v_lshlrev_b32_e32 v172, 16, v61
	v_fmac_f32_e32 v115, v171, v171
	v_and_b32_e32 v173, 0xffff0000, v61
	v_fmac_f32_e32 v115, v172, v172
	v_and_b32_e32 v142, 0xffff0000, v62
	v_lshlrev_b32_e32 v143, 16, v62
	v_fmac_f32_e32 v115, v173, v173
	v_pk_mul_f32 v[116:117], v[142:143], v[142:143]
	v_and_b32_e32 v144, 0xffff0000, v63
	v_add_f32_e32 v115, v117, v115
	v_lshlrev_b32_e32 v145, 16, v63
	v_add_f32_e32 v115, v116, v115
	v_pk_mul_f32 v[116:117], v[144:145], v[144:145]
	v_lshlrev_b32_e32 v112, 16, v32
	v_add_f32_e32 v115, v117, v115
	v_add_f32_e32 v115, v116, v115
	ds_bpermute_b32 v116, v96, v115
	v_and_b32_e32 v114, 0xffff0000, v32
	v_lshlrev_b32_e32 v113, 16, v33
	v_and_b32_e32 v111, 0xffff0000, v33
	v_lshlrev_b32_e32 v110, 16, v34
	s_waitcnt lgkmcnt(0)
	v_add_f32_e32 v115, v115, v116
	ds_bpermute_b32 v116, v104, v115
	v_and_b32_e32 v141, 0xffff0000, v34
	v_lshlrev_b32_e32 v140, 16, v35
	v_and_b32_e32 v138, 0xffff0000, v35
	v_lshlrev_b32_e32 v136, 16, v36
	s_waitcnt lgkmcnt(0)
	v_add_f32_e32 v115, v115, v116
	ds_bpermute_b32 v116, v105, v115
	v_and_b32_e32 v139, 0xffff0000, v36
	v_lshlrev_b32_e32 v137, 16, v37
	v_and_b32_e32 v134, 0xffff0000, v37
	v_lshlrev_b32_e32 v132, 16, v38
	s_waitcnt lgkmcnt(0)
	v_add_f32_e32 v115, v115, v116
	ds_bpermute_b32 v116, v106, v115
	v_and_b32_e32 v135, 0xffff0000, v38
	v_lshlrev_b32_e32 v133, 16, v39
	v_and_b32_e32 v130, 0xffff0000, v39
	v_lshlrev_b32_e32 v127, 16, v48
	s_waitcnt lgkmcnt(0)
	v_add_f32_e32 v115, v115, v116
	ds_bpermute_b32 v116, v107, v115
	v_and_b32_e32 v131, 0xffff0000, v48
	v_lshlrev_b32_e32 v128, 16, v49
	v_and_b32_e32 v124, 0xffff0000, v49
	v_lshlrev_b32_e32 v121, 16, v50
	s_waitcnt lgkmcnt(0)
	v_add_f32_e32 v123, v115, v116
	ds_bpermute_b32 v126, v108, v123
	v_and_b32_e32 v125, 0xffff0000, v50
	v_lshlrev_b32_e32 v122, 16, v51
	v_and_b32_e32 v119, 0xffff0000, v51
	v_lshlrev_b32_e32 v117, 16, v52
	s_waitcnt lgkmcnt(0)
	v_add_f32_e32 v123, v123, v126
	v_fmamk_f32 v123, v123, 0x3a000000, v109
	v_mul_f32_e32 v126, 0x4b800000, v123
	v_cmp_gt_f32_e32 vcc, s12, v123
	v_and_b32_e32 v120, 0xffff0000, v52
	v_and_b32_e32 v129, 0xffff0000, v54
	v_cndmask_b32_e32 v123, v123, v126, vcc
	v_rsq_f32_e32 v174, v123
	v_lshlrev_b32_e32 v118, 16, v53
	v_lshlrev_b32_e32 v126, 16, v55
	v_and_b32_e32 v116, 0xffff0000, v53
	v_mul_f32_e32 v175, 0x45800000, v174
	v_cndmask_b32_e32 v174, v174, v175, vcc
	v_mul_f32_e32 v146, v174, v146
	v_fmac_f32_e32 v112, v8, v146
	v_mul_f32_e32 v146, v174, v147
	v_fmac_f32_e32 v114, v9, v146
	v_mul_f32_e32 v146, v174, v148
	v_fmac_f32_e32 v113, v10, v146
	v_mul_f32_e32 v146, v174, v149
	v_fmac_f32_e32 v111, v11, v146
	v_mul_f32_e32 v146, v174, v150
	v_fmac_f32_e32 v110, v0, v146
	v_mul_f32_e32 v146, v174, v151
	v_fmac_f32_e32 v141, v1, v146
	v_mul_f32_e32 v146, v174, v152
	v_fmac_f32_e32 v140, v2, v146
	v_mul_f32_e32 v146, v174, v153
	v_fmac_f32_e32 v138, v3, v146
	v_mul_f32_e32 v146, v174, v154
	v_fmac_f32_e32 v136, v4, v146
	v_mul_f32_e32 v146, v174, v155
	v_fmac_f32_e32 v139, v5, v146
	v_mul_f32_e32 v146, v174, v156
	v_fmac_f32_e32 v137, v6, v146
	v_mul_f32_e32 v146, v174, v157
	v_fmac_f32_e32 v134, v7, v146
	v_mul_f32_e32 v146, v174, v158
	v_fmac_f32_e32 v132, v12, v146
	v_mul_f32_e32 v146, v174, v159
	v_fmac_f32_e32 v135, v13, v146
	v_mul_f32_e32 v146, v174, v160
	v_fmac_f32_e32 v133, v14, v146
	v_mul_f32_e32 v146, v174, v161
	v_fmac_f32_e32 v130, v15, v146
	v_mul_f32_e32 v146, v174, v162
	v_fmac_f32_e32 v127, v16, v146
	v_mul_f32_e32 v146, v174, v163
	v_fmac_f32_e32 v131, v17, v146
	v_mul_f32_e32 v146, v174, v164
	v_fmac_f32_e32 v128, v18, v146
	v_mul_f32_e32 v146, v174, v165
	v_fmac_f32_e32 v124, v19, v146
	v_mul_f32_e32 v146, v174, v166
	v_fmac_f32_e32 v121, v20, v146
	v_mul_f32_e32 v146, v174, v167
	v_fmac_f32_e32 v125, v21, v146
	v_mul_f32_e32 v146, v174, v168
	v_fmac_f32_e32 v122, v22, v146
	v_mul_f32_e32 v146, v174, v169
	v_fmac_f32_e32 v119, v23, v146
	v_mul_f32_e32 v146, v174, v170
	v_fmac_f32_e32 v117, v24, v146
	v_mul_f32_e32 v146, v174, v171
	v_mul_f32_e32 v142, v174, v142
	v_fmac_f32_e32 v120, v25, v146
	v_mul_f32_e32 v146, v174, v172
	v_fmac_f32_e32 v129, v29, v142
	v_mul_f32_e32 v142, v174, v145
	v_lshlrev_b32_e32 v115, 16, v54
	v_and_b32_e32 v123, 0xffff0000, v55
	v_fmac_f32_e32 v118, v26, v146
	v_mul_f32_e32 v146, v174, v173
	v_mul_f32_e32 v143, v174, v143
	v_fmac_f32_e32 v126, v30, v142
	v_mul_f32_e32 v142, v174, v144
	v_fmac_f32_e32 v116, v27, v146
	v_fmac_f32_e32 v115, v28, v143
	s_and_b64 vcc, exec, s[2:3]
	v_fmac_f32_e32 v123, v31, v142
	s_cbranch_vccnz .LBB0_487
	s_mov_b32 s7, s5
	s_lshl_b64 s[8:9], s[6:7], 13
	v_cvt_pk_bf16_f32 v142, v112, v114
	v_cvt_pk_bf16_f32 v143, v113, v111
	v_cvt_pk_bf16_f32 v144, v110, v141
	v_cvt_pk_bf16_f32 v145, v140, v138
	v_lshl_add_u64 v[146:147], v[98:99], 0, s[8:9]
	global_store_dwordx4 v[146:147], v[142:145], off nt
	s_nop 1
	v_cvt_pk_bf16_f32 v142, v136, v139
	v_cvt_pk_bf16_f32 v143, v137, v134
	v_cvt_pk_bf16_f32 v144, v132, v135
	v_cvt_pk_bf16_f32 v145, v133, v130
	global_store_dwordx4 v[146:147], v[142:145], off offset:1024 nt
	s_nop 1
	v_cvt_pk_bf16_f32 v142, v127, v131
	v_cvt_pk_bf16_f32 v143, v128, v124
	v_cvt_pk_bf16_f32 v144, v121, v125
	v_cvt_pk_bf16_f32 v145, v122, v119
	global_store_dwordx4 v[146:147], v[142:145], off offset:2048 nt
	s_nop 1
	v_cvt_pk_bf16_f32 v142, v117, v120
	v_cvt_pk_bf16_f32 v143, v118, v116
	v_cvt_pk_bf16_f32 v144, v115, v129
	v_cvt_pk_bf16_f32 v145, v126, v123
	global_store_dwordx4 v[146:147], v[142:145], off offset:3072 nt

.LBB0_491:
	s_waitcnt vmcnt(18)
	v_and_b32_e32 v116, 0xffff0000, v92
	v_lshlrev_b32_e32 v113, 16, v92
	v_mul_f32_e32 v92, v116, v116
	v_lshlrev_b32_e32 v117, 16, v93
	v_fmac_f32_e32 v92, v113, v113
	v_and_b32_e32 v118, 0xffff0000, v93
	v_fmac_f32_e32 v92, v117, v117
	v_lshlrev_b32_e32 v119, 16, v94
	v_fmac_f32_e32 v92, v118, v118
	v_and_b32_e32 v120, 0xffff0000, v94
	v_fmac_f32_e32 v92, v119, v119
	v_lshlrev_b32_e32 v121, 16, v95
	v_fmac_f32_e32 v92, v120, v120
	v_and_b32_e32 v122, 0xffff0000, v95
	v_fmac_f32_e32 v92, v121, v121
	v_fmac_f32_e32 v92, v122, v122
	s_waitcnt vmcnt(17)
	v_lshlrev_b32_e32 v123, 16, v88
	v_and_b32_e32 v124, 0xffff0000, v88
	v_fmac_f32_e32 v92, v123, v123
	v_lshlrev_b32_e32 v125, 16, v89
	v_fmac_f32_e32 v92, v124, v124
	v_and_b32_e32 v126, 0xffff0000, v89
	v_fmac_f32_e32 v92, v125, v125
	v_lshlrev_b32_e32 v127, 16, v90
	v_fmac_f32_e32 v92, v126, v126
	v_and_b32_e32 v128, 0xffff0000, v90
	v_fmac_f32_e32 v92, v127, v127
	v_lshlrev_b32_e32 v129, 16, v91
	v_fmac_f32_e32 v92, v128, v128
	v_and_b32_e32 v130, 0xffff0000, v91
	v_fmac_f32_e32 v92, v129, v129
	v_fmac_f32_e32 v92, v130, v130
	s_waitcnt vmcnt(14)
	v_lshlrev_b32_e32 v131, 16, v84
	v_and_b32_e32 v132, 0xffff0000, v84
	v_fmac_f32_e32 v92, v131, v131
	v_lshlrev_b32_e32 v133, 16, v85
	v_fmac_f32_e32 v92, v132, v132
	v_and_b32_e32 v134, 0xffff0000, v85
	v_fmac_f32_e32 v92, v133, v133
	v_lshlrev_b32_e32 v135, 16, v86
	v_fmac_f32_e32 v92, v134, v134
	v_and_b32_e32 v136, 0xffff0000, v86
	v_fmac_f32_e32 v92, v135, v135
	v_lshlrev_b32_e32 v137, 16, v87
	v_fmac_f32_e32 v92, v136, v136
	v_and_b32_e32 v138, 0xffff0000, v87
	v_fmac_f32_e32 v92, v137, v137
	v_fmac_f32_e32 v92, v138, v138
	s_waitcnt vmcnt(13)
	v_lshlrev_b32_e32 v139, 16, v80
	v_and_b32_e32 v140, 0xffff0000, v80
	v_fmac_f32_e32 v92, v139, v139
	v_lshlrev_b32_e32 v141, 16, v81
	v_fmac_f32_e32 v92, v140, v140
	v_and_b32_e32 v142, 0xffff0000, v81
	v_fmac_f32_e32 v92, v141, v141
	v_and_b32_e32 v94, 0xffff0000, v82
	v_lshlrev_b32_e32 v95, 16, v82
	v_fmac_f32_e32 v92, v142, v142
	v_pk_mul_f32 v[80:81], v[94:95], v[94:95]
	v_and_b32_e32 v114, 0xffff0000, v83
	v_add_f32_e32 v81, v81, v92
	v_lshlrev_b32_e32 v115, 16, v83
	v_add_f32_e32 v82, v80, v81
	v_pk_mul_f32 v[80:81], v[114:115], v[114:115]
	v_lshlrev_b32_e32 v110, 16, v76
	v_add_f32_e32 v81, v81, v82
	v_add_f32_e32 v80, v80, v81
	ds_bpermute_b32 v81, v96, v80
	v_and_b32_e32 v112, 0xffff0000, v76
	v_lshlrev_b32_e32 v76, 16, v78
	v_and_b32_e32 v93, 0xffff0000, v78
	v_lshlrev_b32_e32 v92, 16, v79
	s_waitcnt lgkmcnt(0)
	v_add_f32_e32 v78, v80, v81
	v_and_b32_e32 v90, 0xffff0000, v79
	ds_bpermute_b32 v79, v104, v78
	v_lshlrev_b32_e32 v88, 16, v72
	v_and_b32_e32 v91, 0xffff0000, v72
	v_lshlrev_b32_e32 v89, 16, v73
	v_and_b32_e32 v86, 0xffff0000, v73
	s_waitcnt lgkmcnt(0)
	v_add_f32_e32 v72, v78, v79
	ds_bpermute_b32 v73, v105, v72
	v_lshlrev_b32_e32 v85, 16, v75
	v_and_b32_e32 v82, 0xffff0000, v75
	v_lshlrev_b32_e32 v84, 16, v74
	v_and_b32_e32 v87, 0xffff0000, v74
	s_waitcnt lgkmcnt(0)
	v_add_f32_e32 v73, v72, v73
	ds_bpermute_b32 v75, v106, v73
	v_lshlrev_b32_e32 v80, 16, v69
	v_and_b32_e32 v74, 0xffff0000, v69
	v_lshlrev_b32_e32 v79, 16, v68
	v_and_b32_e32 v83, 0xffff0000, v68
	s_waitcnt lgkmcnt(0)
	v_add_f32_e32 v69, v73, v75
	ds_bpermute_b32 v78, v107, v69
	v_lshlrev_b32_e32 v72, 16, v70
	v_and_b32_e32 v75, 0xffff0000, v70
	v_lshlrev_b32_e32 v73, 16, v71
	v_and_b32_e32 v70, 0xffff0000, v71
	s_waitcnt lgkmcnt(0)
	v_add_f32_e32 v78, v69, v78
	ds_bpermute_b32 v81, v108, v78
	v_lshlrev_b32_e32 v68, 16, v64
	v_and_b32_e32 v71, 0xffff0000, v64
	v_lshlrev_b32_e32 v64, 16, v66
	v_lshlrev_b32_e32 v111, 16, v77
	s_waitcnt lgkmcnt(0)
	v_add_f32_e32 v78, v78, v81
	v_fmamk_f32 v78, v78, 0x3a000000, v109
	v_mul_f32_e32 v81, 0x4b800000, v78
	v_cmp_gt_f32_e32 vcc, s12, v78
	v_and_b32_e32 v77, 0xffff0000, v77
	v_lshlrev_b32_e32 v69, 16, v65
	v_cndmask_b32_e32 v78, v78, v81, vcc
	v_rsq_f32_e32 v143, v78
	v_and_b32_e32 v81, 0xffff0000, v66
	v_lshlrev_b32_e32 v78, 16, v67
	v_and_b32_e32 v66, 0xffff0000, v67
	v_mul_f32_e32 v67, 0x45800000, v143
	v_cndmask_b32_e32 v67, v143, v67, vcc
	v_mul_f32_e32 v113, v67, v113
	v_fmac_f32_e32 v110, v8, v113
	v_mul_f32_e32 v113, v67, v116
	v_fmac_f32_e32 v112, v9, v113
	v_mul_f32_e32 v113, v67, v117
	v_fmac_f32_e32 v111, v10, v113
	v_mul_f32_e32 v113, v67, v118
	v_fmac_f32_e32 v77, v11, v113
	v_mul_f32_e32 v113, v67, v119
	v_fmac_f32_e32 v76, v0, v113
	v_mul_f32_e32 v113, v67, v120
	v_fmac_f32_e32 v93, v1, v113
	v_mul_f32_e32 v113, v67, v121
	v_fmac_f32_e32 v92, v2, v113
	v_mul_f32_e32 v113, v67, v122
	v_fmac_f32_e32 v90, v3, v113
	v_mul_f32_e32 v113, v67, v123
	v_fmac_f32_e32 v88, v4, v113
	v_mul_f32_e32 v113, v67, v124
	v_fmac_f32_e32 v91, v5, v113
	v_mul_f32_e32 v113, v67, v125
	v_fmac_f32_e32 v89, v6, v113
	v_mul_f32_e32 v113, v67, v126
	v_fmac_f32_e32 v86, v7, v113
	v_mul_f32_e32 v113, v67, v127
	v_fmac_f32_e32 v84, v12, v113
	v_mul_f32_e32 v113, v67, v128
	v_fmac_f32_e32 v87, v13, v113
	v_mul_f32_e32 v113, v67, v129
	v_fmac_f32_e32 v85, v14, v113
	v_mul_f32_e32 v113, v67, v130
	v_fmac_f32_e32 v82, v15, v113
	v_mul_f32_e32 v113, v67, v131
	v_fmac_f32_e32 v79, v16, v113
	v_mul_f32_e32 v113, v67, v132
	v_fmac_f32_e32 v83, v17, v113
	v_mul_f32_e32 v113, v67, v133
	v_fmac_f32_e32 v80, v18, v113
	v_mul_f32_e32 v113, v67, v134
	v_fmac_f32_e32 v74, v19, v113
	v_mul_f32_e32 v113, v67, v135
	v_fmac_f32_e32 v72, v20, v113
	v_mul_f32_e32 v113, v67, v136
	v_fmac_f32_e32 v75, v21, v113
	v_mul_f32_e32 v113, v67, v137
	v_fmac_f32_e32 v73, v22, v113
	v_mul_f32_e32 v113, v67, v138
	v_fmac_f32_e32 v70, v23, v113
	v_mul_f32_e32 v113, v67, v139
	v_fmac_f32_e32 v68, v24, v113
	v_mul_f32_e32 v113, v67, v140
	v_fmac_f32_e32 v71, v25, v113
	v_mul_f32_e32 v113, v67, v141
	v_mul_f32_e32 v94, v67, v94
	v_and_b32_e32 v65, 0xffff0000, v65
	v_fmac_f32_e32 v69, v26, v113
	v_mul_f32_e32 v113, v67, v142
	v_mul_f32_e32 v95, v67, v95
	v_fmac_f32_e32 v81, v29, v94
	v_mul_f32_e32 v94, v67, v115
	v_mul_f32_e32 v67, v67, v114
	v_fmac_f32_e32 v65, v27, v113
	v_fmac_f32_e32 v64, v28, v95
	v_fmac_f32_e32 v78, v30, v94
	s_and_b64 vcc, exec, s[2:3]
	v_fmac_f32_e32 v66, v31, v67
	s_cbranch_vccnz .LBB0_493
	v_cvt_pk_bf16_f32 v114, v110, v112
	v_cvt_pk_bf16_f32 v115, v111, v77
	v_cvt_pk_bf16_f32 v116, v76, v93
	v_cvt_pk_bf16_f32 v117, v92, v90
	global_store_dwordx4 v[102:103], v[114:117], off nt
	s_nop 1
	v_cvt_pk_bf16_f32 v114, v88, v91
	v_cvt_pk_bf16_f32 v115, v89, v86
	v_cvt_pk_bf16_f32 v116, v84, v87
	v_cvt_pk_bf16_f32 v117, v85, v82
	global_store_dwordx4 v[102:103], v[114:117], off offset:1024 nt
	s_nop 1
	v_cvt_pk_bf16_f32 v114, v79, v83
	v_cvt_pk_bf16_f32 v115, v80, v74
	v_cvt_pk_bf16_f32 v116, v72, v75
	v_cvt_pk_bf16_f32 v117, v73, v70
	global_store_dwordx4 v[102:103], v[114:117], off offset:2048 nt
	s_nop 1
	v_cvt_pk_bf16_f32 v114, v68, v71
	v_cvt_pk_bf16_f32 v115, v69, v65
	v_cvt_pk_bf16_f32 v116, v64, v81
	v_cvt_pk_bf16_f32 v117, v78, v66
	global_store_dwordx4 v[102:103], v[114:117], off offset:3072 nt
.LBB0_493:
	v_mul_f32_e32 v67, v112, v112
	v_fmac_f32_e32 v67, v110, v110
	v_fmac_f32_e32 v67, v111, v111
	v_fmac_f32_e32 v67, v77, v77
	v_fmac_f32_e32 v67, v76, v76
	v_fmac_f32_e32 v67, v93, v93
	v_fmac_f32_e32 v67, v92, v92
	v_fmac_f32_e32 v67, v90, v90
	v_fmac_f32_e32 v67, v88, v88
	v_fmac_f32_e32 v67, v91, v91
	v_fmac_f32_e32 v67, v89, v89
	v_fmac_f32_e32 v67, v86, v86
	v_fmac_f32_e32 v67, v84, v84
	v_fmac_f32_e32 v67, v87, v87
	v_fmac_f32_e32 v67, v85, v85
	v_fmac_f32_e32 v67, v82, v82
	v_fmac_f32_e32 v67, v79, v79
	v_fmac_f32_e32 v67, v83, v83
	v_fmac_f32_e32 v67, v80, v80
	v_fmac_f32_e32 v67, v74, v74
	v_fmac_f32_e32 v67, v72, v72
	v_fmac_f32_e32 v67, v75, v75
	v_fmac_f32_e32 v67, v73, v73
	v_fmac_f32_e32 v67, v70, v70
	v_fmac_f32_e32 v67, v68, v68
	v_fmac_f32_e32 v67, v71, v71
	v_fmac_f32_e32 v67, v69, v69
	v_fmac_f32_e32 v67, v65, v65
	v_fmac_f32_e32 v67, v64, v64
	v_fmac_f32_e32 v67, v81, v81
	v_fmac_f32_e32 v67, v78, v78
	v_fmac_f32_e32 v67, v66, v66
	ds_bpermute_b32 v64, v96, v67
	s_waitcnt lgkmcnt(0)
	v_add_f32_e32 v64, v67, v64
	ds_bpermute_b32 v65, v104, v64
	s_waitcnt lgkmcnt(0)
	v_add_f32_e32 v64, v64, v65
	ds_bpermute_b32 v65, v105, v64
	s_waitcnt lgkmcnt(0)
	v_add_f32_e32 v64, v64, v65
	ds_bpermute_b32 v65, v106, v64
	s_waitcnt lgkmcnt(0)
	v_add_f32_e32 v64, v64, v65
	ds_bpermute_b32 v65, v107, v64
	s_waitcnt lgkmcnt(0)
	v_add_f32_e32 v64, v64, v65
	ds_bpermute_b32 v65, v108, v64
	s_and_saveexec_b64 s[6:7], s[0:1]
	s_cbranch_execz .LBB0_484
	s_waitcnt lgkmcnt(0)
	v_add_f32_e32 v64, v64, v65
	v_fmamk_f32 v64, v64, 0x3a000000, v109
	v_mul_f32_e32 v65, 0x4b800000, v64
	v_cmp_gt_f32_e32 vcc, s12, v64
	s_lshl_b64 s[8:9], s[4:5], 2
	s_add_u32 s8, s87, s8
	v_cndmask_b32_e32 v64, v64, v65, vcc
	v_rsq_f32_e32 v64, v64
	s_addc_u32 s9, s88, s9
	v_mul_f32_e32 v65, 0x45800000, v64
	v_cndmask_b32_e32 v64, v64, v65, vcc
	global_store_dword v97, v64, s[8:9]
	s_branch .LBB0_484
.Lr11_last:
	s_waitcnt vmcnt(0)
	s_branch .LBB0_491
.LBB0_495:
	s_cmp_lt_i32 s53, 13
	s_cbranch_scc1 .LBB0_505
	s_waitcnt vmcnt(0) lgkmcnt(0)
	s_add_i32 s85, s85, 1
	v_readlane_b32 s0, v242, 0
	s_cmp_gt_u32 s0, 63
	s_waitcnt vmcnt(0) lgkmcnt(0)
	s_barrier
	s_cbranch_scc1 .LBB0_504
	v_mbcnt_lo_u32_b32 v0, -1, 0
	v_mbcnt_hi_u32_b32 v0, -1, v0
	s_nop 0
	v_and_b32_e32 v0, 63, v0
	v_cmp_eq_u32_e32 vcc, 0, v0
	s_and_saveexec_b64 s[0:1], vcc
	s_cbranch_execz .LBB0_503
	s_mov_b64 s[2:3], exec
	buffer_wbl2 sc1
	s_waitcnt vmcnt(0)
	v_mbcnt_lo_u32_b32 v0, s2, 0
	v_mbcnt_hi_u32_b32 v0, s3, v0
	v_cmp_eq_u32_e32 vcc, 0, v0
	s_and_saveexec_b64 s[4:5], vcc
	s_cbranch_execz .LBB0_500
	s_bcnt1_i32_b64 s2, s[2:3]
	v_mov_b32_e32 v0, 0
	v_mov_b32_e32 v1, s2
	global_atomic_add v0, v1, s[82:83]

.LBB0_531:
	v_mbcnt_lo_u32_b32 v69, -1, 0
	v_mbcnt_hi_u32_b32 v69, -1, v69
	s_and_b64 vcc, exec, s[56:57]
	v_add_u32_e32 v64, s64, v69
	v_bfe_u32 v68, v64, 8, 1
	v_ashrrev_i32_e32 v73, 6, v64
	v_bfe_u32 v64, v69, 4, 2
	v_and_b32_e32 v71, 3, v73
	v_and_b32_e32 v70, 15, v69
	v_lshlrev_b32_e32 v72, 4, v64
	s_cbranch_vccz .LBB0_534
	s_lshl_b32 s36, s80, 14
	s_lshl_b32 s37, s78, 22
	s_add_i32 s36, s36, s37
	v_lshlrev_b32_e32 v64, 6, v70
	v_or3_b32 v64, s36, v64, v72
	v_lshl_add_u32 v64, v71, 20, v64
	v_lshl_or_b32 v164, v68, 12, v64
	s_waitcnt vmcnt(14)
	v_pk_mul_f32 v[64:65], v[172:173], v[58:59] op_sel_hi:[0,1]
	v_pk_mul_f32 v[66:67], v[172:173], v[56:57] op_sel_hi:[0,1]
	v_max_f32_e32 v66, 0, v66
	v_max_f32_e32 v64, 0, v64
	v_mul_f32_e32 v74, v66, v66
	v_max_f32_e32 v66, 0, v67
	v_mul_f32_e32 v76, v64, v64
	v_max_f32_e32 v64, 0, v65
	v_mul_f32_e32 v75, v66, v66
	v_mul_f32_e32 v77, v64, v64
	v_pk_mul_f32 v[64:65], v[172:173], v[62:63] op_sel_hi:[0,1]
	v_pk_mul_f32 v[66:67], v[172:173], v[60:61] op_sel_hi:[0,1]
	v_max_f32_e32 v66, 0, v66
	v_max_f32_e32 v64, 0, v64
	v_mul_f32_e32 v66, v66, v66
	v_max_f32_e32 v67, 0, v67
	v_mul_f32_e32 v78, v64, v64
	v_max_f32_e32 v64, 0, v65
	v_mul_f32_e32 v67, v67, v67
	v_mul_f32_e32 v65, v64, v64
	v_cvt_pk_bf16_f32 v64, v66, v67
	v_cvt_pk_bf16_f32 v66, v74, v75
	v_lshl_add_u64 v[74:75], s[0:1], 0, v[164:165]
	v_cvt_pk_bf16_f32 v67, v76, v77
	v_add_co_u32_e32 v76, vcc, s66, v74
	v_cvt_pk_bf16_f32 v65, v78, v65
	s_nop 1
	v_addc_co_u32_e32 v77, vcc, 0, v75, vcc
	global_store_dwordx4 v[76:77], v[64:67], off
	v_add_co_u32_e32 v74, vcc, s75, v74
	s_nop 0
	v_pk_mul_f32 v[64:65], v[172:173], v[50:51] op_sel_hi:[0,1]
	v_max_f32_e32 v64, 0, v64
	v_pk_mul_f32 v[66:67], v[172:173], v[48:49] op_sel_hi:[0,1]
	v_mul_f32_e32 v80, v64, v64
	v_max_f32_e32 v64, 0, v65
	v_max_f32_e32 v66, 0, v66
	v_mul_f32_e32 v81, v64, v64
	v_pk_mul_f32 v[64:65], v[172:173], v[54:55] op_sel_hi:[0,1]
	v_mul_f32_e32 v78, v66, v66
	v_max_f32_e32 v66, 0, v67
	v_max_f32_e32 v64, 0, v64
	v_mul_f32_e32 v79, v66, v66
	v_pk_mul_f32 v[66:67], v[172:173], v[52:53] op_sel_hi:[0,1]
	v_mul_f32_e32 v82, v64, v64
	v_max_f32_e32 v64, 0, v65
	v_max_f32_e32 v66, 0, v66
	v_max_f32_e32 v67, 0, v67
	v_mul_f32_e32 v65, v64, v64
	v_mul_f32_e32 v66, v66, v66
	v_mul_f32_e32 v67, v67, v67
	v_cvt_pk_bf16_f32 v64, v66, v67
	v_cvt_pk_bf16_f32 v65, v82, v65
	v_addc_co_u32_e32 v75, vcc, 0, v75, vcc
	v_cvt_pk_bf16_f32 v66, v78, v79
	v_cvt_pk_bf16_f32 v67, v80, v81
	global_store_dwordx4 v[74:75], v[64:67], off
	s_nop 1
	v_pk_mul_f32 v[64:65], v[170:171], v[42:43] op_sel_hi:[0,1]
	v_max_f32_e32 v64, 0, v64
	v_pk_mul_f32 v[66:67], v[170:171], v[40:41] op_sel_hi:[0,1]
	v_mul_f32_e32 v80, v64, v64
	v_max_f32_e32 v64, 0, v65
	v_max_f32_e32 v66, 0, v66
	v_mul_f32_e32 v81, v64, v64
	v_pk_mul_f32 v[64:65], v[170:171], v[46:47] op_sel_hi:[0,1]
	v_mul_f32_e32 v78, v66, v66
	v_max_f32_e32 v66, 0, v67
	v_max_f32_e32 v64, 0, v64
	v_mul_f32_e32 v79, v66, v66
	v_pk_mul_f32 v[66:67], v[170:171], v[44:45] op_sel_hi:[0,1]
	v_mul_f32_e32 v82, v64, v64
	v_max_f32_e32 v64, 0, v65
	v_max_f32_e32 v66, 0, v66
	v_max_f32_e32 v67, 0, v67
	v_mul_f32_e32 v65, v64, v64
	v_mul_f32_e32 v66, v66, v66
	v_mul_f32_e32 v67, v67, v67
	v_cvt_pk_bf16_f32 v64, v66, v67
	v_cvt_pk_bf16_f32 v65, v82, v65
	v_cvt_pk_bf16_f32 v66, v78, v79
	v_cvt_pk_bf16_f32 v67, v80, v81
	global_store_dwordx4 v[76:77], v[64:67], off offset:1024
	s_nop 1
	v_pk_mul_f32 v[64:65], v[170:171], v[26:27] op_sel_hi:[0,1]
	v_max_f32_e32 v64, 0, v64
	v_pk_mul_f32 v[66:67], v[170:171], v[24:25] op_sel_hi:[0,1]
	v_mul_f32_e32 v80, v64, v64
	v_max_f32_e32 v64, 0, v65
	v_max_f32_e32 v66, 0, v66
	v_mul_f32_e32 v81, v64, v64
	v_pk_mul_f32 v[64:65], v[170:171], v[30:31] op_sel_hi:[0,1]
	v_mul_f32_e32 v78, v66, v66
	v_max_f32_e32 v66, 0, v67
	v_max_f32_e32 v64, 0, v64
	v_mul_f32_e32 v79, v66, v66
	v_pk_mul_f32 v[66:67], v[170:171], v[28:29] op_sel_hi:[0,1]
	v_mul_f32_e32 v82, v64, v64
	v_max_f32_e32 v64, 0, v65
	v_max_f32_e32 v66, 0, v66
	v_max_f32_e32 v67, 0, v67
	v_mul_f32_e32 v65, v64, v64
	v_mul_f32_e32 v66, v66, v66
	v_mul_f32_e32 v67, v67, v67
	v_cvt_pk_bf16_f32 v64, v66, v67
	v_cvt_pk_bf16_f32 v65, v82, v65
	v_cvt_pk_bf16_f32 v66, v78, v79
	v_cvt_pk_bf16_f32 v67, v80, v81
	global_store_dwordx4 v[74:75], v[64:67], off offset:1024
	s_nop 1
	v_pk_mul_f32 v[64:65], v[168:169], v[34:35] op_sel_hi:[0,1]
	v_max_f32_e32 v64, 0, v64
	v_pk_mul_f32 v[66:67], v[168:169], v[32:33] op_sel_hi:[0,1]
	v_mul_f32_e32 v80, v64, v64
	v_max_f32_e32 v64, 0, v65
	v_max_f32_e32 v66, 0, v66
	v_mul_f32_e32 v81, v64, v64
	v_pk_mul_f32 v[64:65], v[168:169], v[38:39] op_sel_hi:[0,1]
	v_mul_f32_e32 v78, v66, v66
	v_max_f32_e32 v66, 0, v67
	v_max_f32_e32 v64, 0, v64
	v_mul_f32_e32 v79, v66, v66
	v_pk_mul_f32 v[66:67], v[168:169], v[36:37] op_sel_hi:[0,1]
	v_mul_f32_e32 v82, v64, v64
	v_max_f32_e32 v64, 0, v65
	v_max_f32_e32 v66, 0, v66
	v_max_f32_e32 v67, 0, v67
	v_mul_f32_e32 v65, v64, v64
	v_mul_f32_e32 v66, v66, v66
	v_mul_f32_e32 v67, v67, v67
	v_cvt_pk_bf16_f32 v64, v66, v67
	v_cvt_pk_bf16_f32 v65, v82, v65
	v_cvt_pk_bf16_f32 v66, v78, v79
	v_cvt_pk_bf16_f32 v67, v80, v81
	global_store_dwordx4 v[76:77], v[64:67], off offset:2048
	s_nop 1
	v_pk_mul_f32 v[64:65], v[168:169], v[18:19] op_sel_hi:[0,1]
	v_max_f32_e32 v64, 0, v64
	v_pk_mul_f32 v[66:67], v[168:169], v[16:17] op_sel_hi:[0,1]
	v_mul_f32_e32 v80, v64, v64
	v_max_f32_e32 v64, 0, v65
	v_max_f32_e32 v66, 0, v66
	v_mul_f32_e32 v81, v64, v64
	v_pk_mul_f32 v[64:65], v[168:169], v[22:23] op_sel_hi:[0,1]
	v_mul_f32_e32 v78, v66, v66
	v_max_f32_e32 v66, 0, v67
	v_max_f32_e32 v64, 0, v64
	v_mul_f32_e32 v79, v66, v66
	v_pk_mul_f32 v[66:67], v[168:169], v[20:21] op_sel_hi:[0,1]
	v_mul_f32_e32 v82, v64, v64
	v_max_f32_e32 v64, 0, v65
	v_max_f32_e32 v66, 0, v66
	v_max_f32_e32 v67, 0, v67
	v_mul_f32_e32 v65, v64, v64
	v_mul_f32_e32 v66, v66, v66
	v_mul_f32_e32 v67, v67, v67
	v_cvt_pk_bf16_f32 v64, v66, v67
	v_cvt_pk_bf16_f32 v65, v82, v65
	v_cvt_pk_bf16_f32 v66, v78, v79
	v_cvt_pk_bf16_f32 v67, v80, v81
	global_store_dwordx4 v[74:75], v[64:67], off offset:2048
	s_nop 1
	v_pk_mul_f32 v[64:65], v[166:167], v[10:11] op_sel_hi:[0,1]
	v_max_f32_e32 v64, 0, v64
	v_pk_mul_f32 v[66:67], v[166:167], v[8:9] op_sel_hi:[0,1]
	v_mul_f32_e32 v78, v64, v64
	v_max_f32_e32 v64, 0, v65
	v_max_f32_e32 v66, 0, v66
	v_mul_f32_e32 v79, v64, v64
	v_pk_mul_f32 v[64:65], v[166:167], v[14:15] op_sel_hi:[0,1]
	v_mul_f32_e32 v74, v66, v66
	v_max_f32_e32 v66, 0, v67
	v_max_f32_e32 v64, 0, v64
	v_mul_f32_e32 v75, v66, v66
	v_pk_mul_f32 v[66:67], v[166:167], v[12:13] op_sel_hi:[0,1]
	v_mul_f32_e32 v80, v64, v64
	v_max_f32_e32 v64, 0, v65
	v_max_f32_e32 v66, 0, v66
	v_max_f32_e32 v67, 0, v67
	v_mul_f32_e32 v65, v64, v64
	v_mul_f32_e32 v66, v66, v66
	v_mul_f32_e32 v67, v67, v67
	v_cvt_pk_bf16_f32 v64, v66, v67
	v_cvt_pk_bf16_f32 v65, v80, v65
	v_cvt_pk_bf16_f32 v66, v74, v75
	v_cvt_pk_bf16_f32 v67, v78, v79
	global_store_dwordx4 v[76:77], v[64:67], off offset:3072
	s_nop 1
	v_pk_mul_f32 v[64:65], v[166:167], v[2:3] op_sel_hi:[0,1]
	v_pk_mul_f32 v[66:67], v[166:167], v[0:1] op_sel_hi:[0,1]
	v_max_f32_e32 v64, 0, v64
	v_max_f32_e32 v66, 0, v66
	v_mul_f32_e32 v76, v64, v64
	v_max_f32_e32 v64, 0, v65
	v_mul_f32_e32 v74, v66, v66
	v_max_f32_e32 v66, 0, v67
	v_mul_f32_e32 v77, v64, v64
	v_pk_mul_f32 v[64:65], v[166:167], v[6:7] op_sel_hi:[0,1]
	v_mul_f32_e32 v75, v66, v66
	v_pk_mul_f32 v[66:67], v[166:167], v[4:5] op_sel_hi:[0,1]
	v_max_f32_e32 v64, 0, v64
	v_max_f32_e32 v66, 0, v66
	v_max_f32_e32 v67, 0, v67
	v_mul_f32_e32 v78, v64, v64
	v_max_f32_e32 v64, 0, v65
	v_mul_f32_e32 v66, v66, v66
	v_mul_f32_e32 v67, v67, v67
	v_mul_f32_e32 v65, v64, v64
	v_cvt_pk_bf16_f32 v64, v66, v67
	v_cvt_pk_bf16_f32 v65, v78, v65
	v_cvt_pk_bf16_f32 v66, v74, v75
	v_cvt_pk_bf16_f32 v67, v76, v77
	v_add_u32_e32 v74, 0x82c00, v164
	s_cbranch_execnz .LBB0_509
	s_branch .LBB0_508

.LBB0_579:
	s_cmp_lt_i32 s52, 15
	s_cselect_b64 s[0:1], -1, 0
	s_cmp_gt_i32 s53, 14
	s_cselect_b64 s[2:3], -1, 0
	s_and_b64 s[0:1], s[0:1], s[2:3]
	s_andn2_b64 vcc, exec, s[0:1]
	s_cbranch_vccnz .LBB0_599
	s_lshl_b32 s0, s33, 3
	v_readlane_b32 s1, v242, 1
	s_waitcnt lgkmcnt(0)
	s_add_i32 s12, s0, s1
	s_cmpk_gt_u32 s12, 0x1fff
	v_mbcnt_lo_u32_b32 v0, -1, 0
	v_mbcnt_hi_u32_b32 v0, -1, v0
	s_cbranch_scc1 .LBB0_589
	v_lshlrev_b32_e32 v0, 3, v0
	s_waitcnt vmcnt(0)
	v_and_b32_e32 v96, 0x1f8, v0
	v_mov_b32_e32 v99, 0
	v_lshlrev_b32_e32 v98, 2, v96
	v_lshl_add_u64 v[16:17], s[42:43], 0, v[98:99]
	s_mov_b64 s[4:5], 0x2000
	s_mov_b32 s3, 0
	v_lshl_add_u64 v[32:33], v[16:17], 0, s[4:5]
	s_mov_b64 s[4:5], 0x3800
	s_add_u32 s0, s54, 0x2000000
	v_lshl_add_u64 v[18:19], v[16:17], 0, s[4:5]
	s_movk_i32 s2, 0x3000
	s_mov_b64 s[4:5], 0x3000
	s_mov_b32 s13, s3
	s_addc_u32 s1, s55, 0
	s_lshl_b32 s14, s84, 3
	v_add_co_u32_e32 v20, vcc, s2, v16
	v_lshl_add_u64 v[34:35], v[16:17], 0, s[4:5]
	s_lshl_b64 s[4:5], s[12:13], 12
	s_lshl_b64 s[6:7], s[12:13], 13
	v_addc_co_u32_e32 v21, vcc, 0, v17, vcc
	s_movk_i32 s2, 0x2000
	s_add_u32 s6, s40, s6
	v_add_co_u32_e32 v36, vcc, s2, v16
	s_addc_u32 s7, s41, s7
	s_nop 0
	v_addc_co_u32_e32 v37, vcc, 0, v17, vcc
	v_lshlrev_b32_e32 v100, 1, v96
	s_add_u32 s4, s0, s4
	global_load_dwordx4 v[0:3], v[20:21], off offset:2048
	global_load_dwordx4 v[4:7], v[20:21], off
	global_load_dwordx4 v[8:11], v[18:19], off offset:16
	global_load_dwordx4 v[12:15], v[32:33], off offset:2064
	s_nop 0
	global_load_dwordx4 v[16:19], v[34:35], off offset:16
	global_load_dwordx4 v[20:23], v[36:37], off
	global_load_dwordx4 v[24:27], v[32:33], off offset:2048
	global_load_dwordx4 v[28:31], v[32:33], off offset:16
	s_addc_u32 s5, s1, s5
	global_load_dwordx4 v[32:35], v100, s[6:7] nt
	global_load_dwordx4 v[36:39], v100, s[6:7] offset:1024 nt
	global_load_dwordx4 v[40:43], v100, s[4:5] nt
	global_load_dwordx4 v[44:47], v100, s[4:5] offset:1024 nt
	global_load_dwordx4 v[48:51], v100, s[6:7] offset:2048 nt
	global_load_dwordx4 v[52:55], v100, s[6:7] offset:3072 nt
	global_load_dwordx4 v[56:59], v100, s[4:5] offset:2048 nt
	global_load_dwordx4 v[60:63], v100, s[4:5] offset:3072 nt
	v_mbcnt_lo_u32_b32 v64, -1, 0
	v_mbcnt_hi_u32_b32 v64, -1, v64
	v_and_b32_e32 v65, 64, v64
	v_add_u32_e32 v65, 64, v65
	v_xor_b32_e32 v66, 32, v64
	v_cmp_lt_i32_e32 vcc, v66, v65
	v_mov_b32_e32 v101, v99
	s_cmp_lg_u64 s[48:49], 0
	v_cndmask_b32_e32 v66, v64, v66, vcc
	v_lshlrev_b32_e32 v97, 2, v66
	v_xor_b32_e32 v66, 16, v64
	v_cmp_lt_i32_e32 vcc, v66, v65
	v_lshl_add_u64 v[104:105], s[0:1], 0, v[100:101]
	s_cselect_b64 s[0:1], -1, 0
	v_cndmask_b32_e32 v66, v64, v66, vcc
	v_lshlrev_b32_e32 v142, 2, v66
	v_xor_b32_e32 v66, 8, v64
	v_cmp_lt_i32_e32 vcc, v66, v65
	v_lshl_add_u64 v[102:103], s[40:41], 0, v[100:101]
	v_lshl_add_u64 v[106:107], v[102:103], 0, v[100:101]
	v_cndmask_b32_e32 v66, v64, v66, vcc
	v_lshlrev_b32_e32 v143, 2, v66
	v_xor_b32_e32 v66, 4, v64
	v_cmp_lt_i32_e32 vcc, v66, v65
	s_lshl_b32 s15, s84, 4
	v_lshlrev_b32_e32 v108, 1, v96
	v_cndmask_b32_e32 v66, v64, v66, vcc
	v_lshlrev_b32_e32 v144, 2, v66
	v_xor_b32_e32 v66, 2, v64
	v_cmp_lt_i32_e32 vcc, v66, v65
	v_mov_b32_e32 v109, v99
	v_mov_b32_e32 v147, 0x358637bd
	v_cndmask_b32_e32 v66, v64, v66, vcc
	v_lshlrev_b32_e32 v145, 2, v66
	v_xor_b32_e32 v66, 1, v64
	v_cmp_lt_i32_e32 vcc, v66, v65
	s_mov_b32 s16, 0x800000
	s_mov_b64 s[4:5], 0x1000
	v_cndmask_b32_e32 v64, v64, v66, vcc
	v_lshlrev_b32_e32 v146, 2, v64
	v_cndmask_b32_e64 v64, 0, 1, s[0:1]
	v_cmp_ne_u32_e64 s[0:1], 1, v64
	s_movk_i32 s17, 0x1000
	s_mov_b64 s[6:7], 0x1800
	s_waitcnt vmcnt(0)
	s_branch .LBB0_583

.LBB0_583:
	s_add_i32 s2, s12, s14
	s_lshl_b64 s[8:9], s[2:3], 12
	s_lshl_b64 s[10:11], s[2:3], 13
	v_lshl_add_u64 v[64:65], v[102:103], 0, s[10:11]
	v_lshl_add_u64 v[110:111], v[104:105], 0, s[8:9]
	s_add_u32 s8, s40, s10
	global_load_dwordx4 v[64:67], v[64:65], off nt
	s_addc_u32 s9, s41, s11
	global_load_dwordx4 v[92:95], v[110:111], off nt
	global_load_dwordx4 v[88:91], v[110:111], off offset:1024 nt
	global_load_dwordx4 v[68:71], v108, s[8:9] offset:1024 nt
	global_load_dwordx4 v[72:75], v108, s[8:9] offset:2048 nt
	global_load_dwordx4 v[76:79], v108, s[8:9] offset:3072 nt
	global_load_dwordx4 v[84:87], v[110:111], off offset:2048 nt
	global_load_dwordx4 v[80:83], v[110:111], off offset:3072 nt
	s_waitcnt vmcnt(21)
	v_lshlrev_b32_e32 v110, 16, v40
	v_and_b32_e32 v111, 0xffff0000, v40
	v_lshlrev_b32_e32 v112, 16, v41
	v_and_b32_e32 v113, 0xffff0000, v41
	v_pk_mul_f32 v[148:149], v[110:111], v[110:111]
	v_pk_mul_f32 v[150:151], v[112:113], v[112:113]
	v_add_f32_e32 v98, v148, v149
	v_lshlrev_b32_e32 v114, 16, v42
	v_and_b32_e32 v115, 0xffff0000, v42
	v_add_f32_e32 v98, v150, v98
	v_pk_mul_f32 v[152:153], v[114:115], v[114:115]
	v_add_f32_e32 v98, v151, v98
	v_lshlrev_b32_e32 v116, 16, v43
	v_and_b32_e32 v117, 0xffff0000, v43
	v_add_f32_e32 v98, v152, v98
	v_pk_mul_f32 v[154:155], v[116:117], v[116:117]
	v_add_f32_e32 v98, v153, v98
	s_waitcnt vmcnt(20)
	v_lshlrev_b32_e32 v118, 16, v44
	v_and_b32_e32 v119, 0xffff0000, v44
	v_add_f32_e32 v98, v154, v98
	v_pk_mul_f32 v[156:157], v[118:119], v[118:119]
	v_add_f32_e32 v98, v155, v98
	v_lshlrev_b32_e32 v120, 16, v45
	v_and_b32_e32 v121, 0xffff0000, v45
	v_add_f32_e32 v98, v156, v98
	v_pk_mul_f32 v[158:159], v[120:121], v[120:121]
	v_add_f32_e32 v98, v157, v98
	v_lshlrev_b32_e32 v122, 16, v46
	v_and_b32_e32 v123, 0xffff0000, v46
	v_add_f32_e32 v98, v158, v98
	v_pk_mul_f32 v[160:161], v[122:123], v[122:123]
	v_add_f32_e32 v98, v159, v98
	v_lshlrev_b32_e32 v124, 16, v47
	v_and_b32_e32 v125, 0xffff0000, v47
	v_add_f32_e32 v98, v160, v98
	v_pk_mul_f32 v[162:163], v[124:125], v[124:125]
	v_add_f32_e32 v98, v161, v98
	s_waitcnt vmcnt(17)
	v_lshlrev_b32_e32 v126, 16, v56
	s_waitcnt lgkmcnt(0)
	v_and_b32_e32 v127, 0xffff0000, v56
	v_add_f32_e32 v98, v162, v98
	v_pk_mul_f32 v[164:165], v[126:127], v[126:127]
	v_add_f32_e32 v98, v163, v98
	v_lshlrev_b32_e32 v128, 16, v57
	v_and_b32_e32 v129, 0xffff0000, v57
	v_add_f32_e32 v98, v164, v98
	v_pk_mul_f32 v[166:167], v[128:129], v[128:129]
	v_add_f32_e32 v98, v165, v98
	v_lshlrev_b32_e32 v130, 16, v58
	v_and_b32_e32 v131, 0xffff0000, v58
	v_add_f32_e32 v98, v166, v98
	v_pk_mul_f32 v[168:169], v[130:131], v[130:131]
	v_add_f32_e32 v98, v167, v98
	v_lshlrev_b32_e32 v132, 16, v59
	v_and_b32_e32 v133, 0xffff0000, v59
	v_add_f32_e32 v98, v168, v98
	v_pk_mul_f32 v[170:171], v[132:133], v[132:133]
	v_add_f32_e32 v98, v169, v98
	s_waitcnt vmcnt(16)
	v_lshlrev_b32_e32 v134, 16, v60
	v_and_b32_e32 v135, 0xffff0000, v60
	v_add_f32_e32 v98, v170, v98
	v_pk_mul_f32 v[172:173], v[134:135], v[134:135]
	v_add_f32_e32 v98, v171, v98
	v_lshlrev_b32_e32 v136, 16, v61
	v_and_b32_e32 v137, 0xffff0000, v61
	v_add_f32_e32 v98, v172, v98
	v_pk_mul_f32 v[174:175], v[136:137], v[136:137]
	v_add_f32_e32 v98, v173, v98
	v_lshlrev_b32_e32 v138, 16, v62
	v_and_b32_e32 v139, 0xffff0000, v62
	v_add_f32_e32 v98, v174, v98
	v_pk_mul_f32 v[176:177], v[138:139], v[138:139]
	v_add_f32_e32 v98, v175, v98
	v_lshlrev_b32_e32 v140, 16, v63
	v_and_b32_e32 v141, 0xffff0000, v63
	v_add_f32_e32 v98, v176, v98
	v_pk_mul_f32 v[178:179], v[140:141], v[140:141]
	v_add_f32_e32 v98, v177, v98
	v_add_f32_e32 v98, v178, v98
	v_add_f32_e32 v98, v179, v98
	ds_bpermute_b32 v148, v97, v98
	s_and_b64 vcc, exec, s[0:1]
	s_waitcnt lgkmcnt(0)
	v_add_f32_e32 v98, v98, v148
	ds_bpermute_b32 v148, v142, v98
	s_waitcnt lgkmcnt(0)
	v_add_f32_e32 v98, v98, v148
	ds_bpermute_b32 v148, v143, v98
	s_waitcnt lgkmcnt(0)
	v_add_f32_e32 v98, v98, v148
	ds_bpermute_b32 v148, v144, v98
	s_waitcnt lgkmcnt(0)
	v_add_f32_e32 v98, v98, v148
	ds_bpermute_b32 v148, v145, v98
	s_waitcnt lgkmcnt(0)
	v_add_f32_e32 v148, v98, v148
	ds_bpermute_b32 v149, v146, v148
	v_lshlrev_b32_e32 v98, 2, v96
	s_cbranch_vccnz .LBB0_585
	s_waitcnt lgkmcnt(0)
	v_add_f32_e32 v148, v148, v149
	v_fmamk_f32 v148, v148, 0x3a000000, v147
	v_mul_f32_e32 v149, 0x4b800000, v148
	v_cmp_gt_f32_e32 vcc, s16, v148
	s_mov_b32 s13, s3
	s_lshl_b64 s[18:19], s[12:13], 13
	v_cndmask_b32_e32 v148, v148, v149, vcc
	v_rsq_f32_e32 v150, v148
	v_lshlrev_b32_e32 v148, 16, v55
	v_and_b32_e32 v149, 0xffff0000, v55
	v_mul_f32_e32 v151, 0x45800000, v150
	v_cndmask_b32_e32 v150, v150, v151, vcc
	v_pk_mul_f32 v[140:141], v[150:151], v[140:141] op_sel_hi:[0,1]
	v_pk_fma_f32 v[140:141], v[10:11], v[140:141], v[148:149]
	v_lshlrev_b32_e32 v148, 16, v54
	v_and_b32_e32 v149, 0xffff0000, v54
	v_pk_mul_f32 v[138:139], v[150:151], v[138:139] op_sel_hi:[0,1]
	v_pk_fma_f32 v[138:139], v[8:9], v[138:139], v[148:149]
	v_lshlrev_b32_e32 v148, 16, v53
	v_and_b32_e32 v149, 0xffff0000, v53
	v_pk_mul_f32 v[136:137], v[150:151], v[136:137] op_sel_hi:[0,1]
	v_pk_fma_f32 v[136:137], v[2:3], v[136:137], v[148:149]
	v_lshlrev_b32_e32 v148, 16, v52
	v_and_b32_e32 v149, 0xffff0000, v52
	v_pk_mul_f32 v[134:135], v[150:151], v[134:135] op_sel_hi:[0,1]
	v_pk_fma_f32 v[134:135], v[0:1], v[134:135], v[148:149]
	v_lshlrev_b32_e32 v148, 16, v51
	v_and_b32_e32 v149, 0xffff0000, v51
	v_pk_mul_f32 v[132:133], v[150:151], v[132:133] op_sel_hi:[0,1]
	v_pk_fma_f32 v[132:133], v[18:19], v[132:133], v[148:149]
	v_lshlrev_b32_e32 v148, 16, v50
	v_and_b32_e32 v149, 0xffff0000, v50
	v_pk_mul_f32 v[130:131], v[150:151], v[130:131] op_sel_hi:[0,1]
	v_pk_fma_f32 v[130:131], v[16:17], v[130:131], v[148:149]
	v_lshlrev_b32_e32 v148, 16, v49
	v_and_b32_e32 v149, 0xffff0000, v49
	v_pk_mul_f32 v[128:129], v[150:151], v[128:129] op_sel_hi:[0,1]
	v_pk_fma_f32 v[128:129], v[6:7], v[128:129], v[148:149]
	v_lshlrev_b32_e32 v148, 16, v48
	v_and_b32_e32 v149, 0xffff0000, v48
	v_pk_mul_f32 v[126:127], v[150:151], v[126:127] op_sel_hi:[0,1]
	v_pk_fma_f32 v[126:127], v[4:5], v[126:127], v[148:149]
	v_lshlrev_b32_e32 v148, 16, v39
	v_and_b32_e32 v149, 0xffff0000, v39
	v_pk_mul_f32 v[124:125], v[150:151], v[124:125] op_sel_hi:[0,1]
	v_pk_fma_f32 v[124:125], v[14:15], v[124:125], v[148:149]
	v_lshlrev_b32_e32 v148, 16, v38
	v_and_b32_e32 v149, 0xffff0000, v38
	v_pk_mul_f32 v[122:123], v[150:151], v[122:123] op_sel_hi:[0,1]
	v_pk_fma_f32 v[122:123], v[12:13], v[122:123], v[148:149]
	v_lshlrev_b32_e32 v148, 16, v37
	v_and_b32_e32 v149, 0xffff0000, v37
	v_pk_mul_f32 v[120:121], v[150:151], v[120:121] op_sel_hi:[0,1]
	v_pk_fma_f32 v[120:121], v[26:27], v[120:121], v[148:149]
	v_lshlrev_b32_e32 v148, 16, v36
	v_and_b32_e32 v149, 0xffff0000, v36
	v_pk_mul_f32 v[118:119], v[150:151], v[118:119] op_sel_hi:[0,1]
	v_pk_fma_f32 v[118:119], v[24:25], v[118:119], v[148:149]
	v_lshlrev_b32_e32 v148, 16, v35
	v_and_b32_e32 v149, 0xffff0000, v35
	v_pk_mul_f32 v[116:117], v[150:151], v[116:117] op_sel_hi:[0,1]
	v_pk_fma_f32 v[116:117], v[30:31], v[116:117], v[148:149]
	v_lshlrev_b32_e32 v148, 16, v34
	v_and_b32_e32 v149, 0xffff0000, v34
	v_pk_mul_f32 v[114:115], v[150:151], v[114:115] op_sel_hi:[0,1]
	v_pk_fma_f32 v[114:115], v[28:29], v[114:115], v[148:149]
	v_lshlrev_b32_e32 v148, 16, v33
	v_and_b32_e32 v149, 0xffff0000, v33
	v_pk_mul_f32 v[112:113], v[150:151], v[112:113] op_sel_hi:[0,1]
	v_pk_fma_f32 v[112:113], v[22:23], v[112:113], v[148:149]
	v_lshlrev_b32_e32 v148, 16, v32
	v_and_b32_e32 v149, 0xffff0000, v32
	v_pk_mul_f32 v[110:111], v[150:151], v[110:111] op_sel_hi:[0,1]
	v_pk_fma_f32 v[110:111], v[20:21], v[110:111], v[148:149]
	v_lshl_add_u64 v[148:149], v[106:107], 0, s[18:19]
	s_add_u32 s18, s40, s18
	s_addc_u32 s19, s41, s19
	global_store_dwordx4 v[148:149], v[110:113], off nt
	global_store_dwordx4 v[148:149], v[114:117], off offset:16 nt
	global_store_dwordx4 v98, v[118:121], s[18:19] offset:2048 nt
	global_store_dwordx4 v98, v[122:125], s[18:19] offset:2064 nt
	v_lshl_add_u64 v[110:111], s[18:19], 0, v[98:99]
	v_add_co_u32_e32 v114, vcc, s17, v110
	v_lshl_add_u64 v[112:113], v[110:111], 0, s[4:5]
	s_nop 0
	v_addc_co_u32_e32 v115, vcc, 0, v111, vcc
	global_store_dwordx4 v[114:115], v[126:129], off nt
	global_store_dwordx4 v[112:113], v[130:133], off offset:16 nt
	v_lshl_add_u64 v[110:111], v[110:111], 0, s[6:7]
	global_store_dwordx4 v[114:115], v[134:137], off offset:2048 nt
	global_store_dwordx4 v[110:111], v[138:141], off offset:16 nt

.LBB0_587:
	s_waitcnt vmcnt(22)
	v_lshlrev_b32_e32 v110, 16, v92
	v_and_b32_e32 v111, 0xffff0000, v92
	v_lshlrev_b32_e32 v92, 16, v93
	v_and_b32_e32 v93, 0xffff0000, v93
	v_pk_mul_f32 v[126:127], v[110:111], v[110:111]
	v_pk_mul_f32 v[128:129], v[92:93], v[92:93]
	v_add_f32_e32 v126, v126, v127
	v_lshlrev_b32_e32 v112, 16, v94
	v_and_b32_e32 v113, 0xffff0000, v94
	v_add_f32_e32 v126, v128, v126
	v_pk_mul_f32 v[130:131], v[112:113], v[112:113]
	v_add_f32_e32 v126, v129, v126
	v_lshlrev_b32_e32 v94, 16, v95
	v_and_b32_e32 v95, 0xffff0000, v95
	v_add_f32_e32 v126, v130, v126
	v_pk_mul_f32 v[132:133], v[94:95], v[94:95]
	v_add_f32_e32 v126, v131, v126
	s_waitcnt vmcnt(21)
	v_lshlrev_b32_e32 v114, 16, v88
	v_and_b32_e32 v115, 0xffff0000, v88
	v_add_f32_e32 v126, v132, v126
	v_pk_mul_f32 v[134:135], v[114:115], v[114:115]
	v_add_f32_e32 v126, v133, v126
	v_lshlrev_b32_e32 v88, 16, v89
	v_and_b32_e32 v89, 0xffff0000, v89
	v_add_f32_e32 v126, v134, v126
	v_pk_mul_f32 v[136:137], v[88:89], v[88:89]
	v_add_f32_e32 v126, v135, v126
	v_lshlrev_b32_e32 v116, 16, v90
	v_and_b32_e32 v117, 0xffff0000, v90
	v_add_f32_e32 v126, v136, v126
	v_pk_mul_f32 v[138:139], v[116:117], v[116:117]
	v_add_f32_e32 v126, v137, v126
	v_lshlrev_b32_e32 v90, 16, v91
	v_and_b32_e32 v91, 0xffff0000, v91
	v_add_f32_e32 v126, v138, v126
	v_pk_mul_f32 v[140:141], v[90:91], v[90:91]
	v_add_f32_e32 v126, v139, v126
	s_waitcnt vmcnt(17)
	v_lshlrev_b32_e32 v118, 16, v84
	v_and_b32_e32 v119, 0xffff0000, v84
	v_add_f32_e32 v126, v140, v126
	s_waitcnt lgkmcnt(0)
	v_pk_mul_f32 v[148:149], v[118:119], v[118:119]
	v_add_f32_e32 v126, v141, v126
	v_lshlrev_b32_e32 v84, 16, v85
	v_and_b32_e32 v85, 0xffff0000, v85
	v_add_f32_e32 v126, v148, v126
	v_pk_mul_f32 v[150:151], v[84:85], v[84:85]
	v_add_f32_e32 v126, v149, v126
	v_lshlrev_b32_e32 v120, 16, v86
	v_and_b32_e32 v121, 0xffff0000, v86
	v_add_f32_e32 v126, v150, v126
	v_pk_mul_f32 v[152:153], v[120:121], v[120:121]
	v_add_f32_e32 v126, v151, v126
	v_lshlrev_b32_e32 v86, 16, v87
	v_and_b32_e32 v87, 0xffff0000, v87
	v_add_f32_e32 v126, v152, v126
	v_pk_mul_f32 v[154:155], v[86:87], v[86:87]
	v_add_f32_e32 v126, v153, v126
	s_waitcnt vmcnt(16)
	v_lshlrev_b32_e32 v122, 16, v80
	v_and_b32_e32 v123, 0xffff0000, v80
	v_add_f32_e32 v126, v154, v126
	v_pk_mul_f32 v[156:157], v[122:123], v[122:123]
	v_add_f32_e32 v126, v155, v126
	v_lshlrev_b32_e32 v80, 16, v81
	v_and_b32_e32 v81, 0xffff0000, v81
	v_add_f32_e32 v126, v156, v126
	v_pk_mul_f32 v[158:159], v[80:81], v[80:81]
	v_add_f32_e32 v126, v157, v126
	v_lshlrev_b32_e32 v124, 16, v82
	v_and_b32_e32 v125, 0xffff0000, v82
	v_add_f32_e32 v126, v158, v126
	v_pk_mul_f32 v[160:161], v[124:125], v[124:125]
	v_add_f32_e32 v126, v159, v126
	v_lshlrev_b32_e32 v82, 16, v83
	v_and_b32_e32 v83, 0xffff0000, v83
	v_add_f32_e32 v126, v160, v126
	v_pk_mul_f32 v[162:163], v[82:83], v[82:83]
	v_add_f32_e32 v126, v161, v126
	v_add_f32_e32 v126, v162, v126
	v_add_f32_e32 v126, v163, v126
	ds_bpermute_b32 v127, v97, v126
	s_and_b64 vcc, exec, s[0:1]
	s_waitcnt lgkmcnt(0)
	v_add_f32_e32 v126, v126, v127
	ds_bpermute_b32 v127, v142, v126
	s_waitcnt lgkmcnt(0)
	v_add_f32_e32 v126, v126, v127
	ds_bpermute_b32 v127, v143, v126
	s_waitcnt lgkmcnt(0)
	v_add_f32_e32 v126, v126, v127
	ds_bpermute_b32 v127, v144, v126
	s_waitcnt lgkmcnt(0)
	v_add_f32_e32 v126, v126, v127
	ds_bpermute_b32 v127, v145, v126
	s_waitcnt lgkmcnt(0)
	v_add_f32_e32 v126, v126, v127
	ds_bpermute_b32 v127, v146, v126
	s_cbranch_vccnz .LBB0_582
	s_waitcnt lgkmcnt(0)
	v_add_f32_e32 v126, v126, v127
	v_fmamk_f32 v126, v126, 0x3a000000, v147
	v_mul_f32_e32 v127, 0x4b800000, v126
	v_cmp_gt_f32_e32 vcc, s16, v126
	v_lshl_add_u64 v[128:129], s[8:9], 0, v[108:109]
	s_nop 0
	v_cndmask_b32_e32 v126, v126, v127, vcc
	v_rsq_f32_e32 v127, v126
	v_lshlrev_b32_e32 v126, 16, v79
	v_mul_f32_e32 v130, 0x45800000, v127
	v_cndmask_b32_e32 v130, v127, v130, vcc
	v_and_b32_e32 v127, 0xffff0000, v79
	v_pk_mul_f32 v[82:83], v[130:131], v[82:83] op_sel_hi:[0,1]
	v_pk_fma_f32 v[126:127], v[10:11], v[82:83], v[126:127]
	v_lshlrev_b32_e32 v82, 16, v78
	v_and_b32_e32 v83, 0xffff0000, v78
	v_pk_mul_f32 v[78:79], v[130:131], v[124:125] op_sel_hi:[0,1]
	v_pk_fma_f32 v[124:125], v[8:9], v[78:79], v[82:83]
	v_lshlrev_b32_e32 v78, 16, v77
	v_and_b32_e32 v79, 0xffff0000, v77
	v_pk_mul_f32 v[80:81], v[130:131], v[80:81] op_sel_hi:[0,1]
	v_pk_fma_f32 v[78:79], v[2:3], v[80:81], v[78:79]
	v_lshlrev_b32_e32 v80, 16, v76
	v_and_b32_e32 v81, 0xffff0000, v76
	v_pk_mul_f32 v[76:77], v[130:131], v[122:123] op_sel_hi:[0,1]
	v_pk_fma_f32 v[76:77], v[0:1], v[76:77], v[80:81]
	v_lshlrev_b32_e32 v80, 16, v75
	v_and_b32_e32 v81, 0xffff0000, v75
	v_pk_mul_f32 v[82:83], v[130:131], v[86:87] op_sel_hi:[0,1]
	v_pk_fma_f32 v[82:83], v[18:19], v[82:83], v[80:81]
	v_lshlrev_b32_e32 v80, 16, v74
	v_and_b32_e32 v81, 0xffff0000, v74
	v_pk_mul_f32 v[74:75], v[130:131], v[120:121] op_sel_hi:[0,1]
	v_pk_fma_f32 v[80:81], v[16:17], v[74:75], v[80:81]
	v_lshlrev_b32_e32 v74, 16, v73
	v_and_b32_e32 v75, 0xffff0000, v73
	v_pk_mul_f32 v[84:85], v[130:131], v[84:85] op_sel_hi:[0,1]
	v_pk_fma_f32 v[74:75], v[6:7], v[84:85], v[74:75]
	v_lshlrev_b32_e32 v84, 16, v72
	v_and_b32_e32 v85, 0xffff0000, v72
	v_pk_mul_f32 v[72:73], v[130:131], v[118:119] op_sel_hi:[0,1]
	v_pk_fma_f32 v[72:73], v[4:5], v[72:73], v[84:85]
	v_lshlrev_b32_e32 v84, 16, v71
	v_and_b32_e32 v85, 0xffff0000, v71
	v_pk_mul_f32 v[86:87], v[130:131], v[90:91] op_sel_hi:[0,1]
	v_pk_fma_f32 v[86:87], v[14:15], v[86:87], v[84:85]
	v_lshlrev_b32_e32 v84, 16, v70
	v_and_b32_e32 v85, 0xffff0000, v70
	v_pk_mul_f32 v[70:71], v[130:131], v[116:117] op_sel_hi:[0,1]
	v_pk_fma_f32 v[84:85], v[12:13], v[70:71], v[84:85]
	v_lshlrev_b32_e32 v70, 16, v69
	v_and_b32_e32 v71, 0xffff0000, v69
	v_pk_mul_f32 v[88:89], v[130:131], v[88:89] op_sel_hi:[0,1]
	v_pk_fma_f32 v[70:71], v[26:27], v[88:89], v[70:71]
	v_lshlrev_b32_e32 v88, 16, v68
	v_and_b32_e32 v89, 0xffff0000, v68
	v_pk_mul_f32 v[68:69], v[130:131], v[114:115] op_sel_hi:[0,1]
	v_pk_fma_f32 v[68:69], v[24:25], v[68:69], v[88:89]
	v_lshlrev_b32_e32 v88, 16, v67
	v_and_b32_e32 v89, 0xffff0000, v67
	v_pk_mul_f32 v[90:91], v[130:131], v[94:95] op_sel_hi:[0,1]
	v_pk_fma_f32 v[90:91], v[30:31], v[90:91], v[88:89]
	v_lshlrev_b32_e32 v88, 16, v66
	v_and_b32_e32 v89, 0xffff0000, v66
	v_pk_mul_f32 v[66:67], v[130:131], v[112:113] op_sel_hi:[0,1]
	v_pk_fma_f32 v[88:89], v[28:29], v[66:67], v[88:89]
	v_lshlrev_b32_e32 v66, 16, v65
	v_and_b32_e32 v67, 0xffff0000, v65
	v_pk_mul_f32 v[92:93], v[130:131], v[92:93] op_sel_hi:[0,1]
	v_pk_fma_f32 v[66:67], v[22:23], v[92:93], v[66:67]
	v_lshlrev_b32_e32 v92, 16, v64
	v_and_b32_e32 v93, 0xffff0000, v64
	v_pk_mul_f32 v[64:65], v[130:131], v[110:111] op_sel_hi:[0,1]
	v_pk_fma_f32 v[64:65], v[20:21], v[64:65], v[92:93]
	v_lshl_add_u64 v[92:93], v[106:107], 0, s[10:11]
	global_store_dwordx4 v[92:93], v[64:67], off nt
	global_store_dwordx4 v[92:93], v[88:91], off offset:16 nt
	s_nop 0
	v_lshl_add_u64 v[64:65], v[128:129], 0, v[100:101]
	global_store_dwordx4 v[64:65], v[68:71], off offset:2048 nt
	global_store_dwordx4 v[64:65], v[84:87], off offset:2064 nt
	v_lshl_add_u64 v[64:65], s[8:9], 0, v[98:99]
	v_add_co_u32_e32 v68, vcc, s17, v64
	v_lshl_add_u64 v[66:67], v[64:65], 0, s[4:5]
	s_nop 0
	v_addc_co_u32_e32 v69, vcc, 0, v65, vcc
	global_store_dwordx4 v[68:69], v[72:75], off nt
	global_store_dwordx4 v[66:67], v[80:83], off offset:16 nt
	v_lshl_add_u64 v[64:65], v[64:65], 0, s[6:7]
	global_store_dwordx4 v[68:69], v[76:79], off offset:2048 nt
	global_store_dwordx4 v[64:65], v[124:127], off offset:16 nt
	s_branch .LBB0_582
.Lr14_last:
	s_waitcnt vmcnt(0)
	s_branch .LBB0_587
.LBB0_589:
	s_cmp_lt_i32 s53, 16
	s_cbranch_scc1 .LBB0_599
	s_waitcnt vmcnt(0) lgkmcnt(0)
	v_readlane_b32 s0, v242, 0
	s_cmp_gt_u32 s0, 63
	s_waitcnt vmcnt(0) lgkmcnt(0)
	s_barrier
	s_cbranch_scc1 .LBB0_598
	v_mbcnt_lo_u32_b32 v0, -1, 0
	v_mbcnt_hi_u32_b32 v0, -1, v0
	s_nop 0
	v_and_b32_e32 v0, 63, v0
	v_cmp_eq_u32_e32 vcc, 0, v0
	s_and_saveexec_b64 s[0:1], vcc
	s_cbranch_execz .LBB0_597
	s_mov_b64 s[2:3], exec
	buffer_wbl2 sc1
	s_waitcnt vmcnt(0)
	v_mbcnt_lo_u32_b32 v0, s2, 0
	v_mbcnt_hi_u32_b32 v0, s3, v0
	v_cmp_eq_u32_e32 vcc, 0, v0
	s_and_saveexec_b64 s[4:5], vcc
	s_cbranch_execz .LBB0_594
	s_bcnt1_i32_b64 s2, s[2:3]
	v_mov_b32_e32 v0, 0
	v_mov_b32_e32 v1, s2
	global_atomic_add v0, v1, s[82:83]
